# v022 + peel waits vmcnt(24) for units>=2 (retest)
# baseline (speedup 1.0000x reference)
.LBB0_183:
	s_ashr_i32 s13, s12, 31
	s_lshl_b64 s[24:25], s[12:13], 19
	s_add_u32 s24, s80, s24
	s_addc_u32 s25, s81, s25
	s_and_b64 s[30:31], s[4:5], exec
	s_cselect_b32 s13, s25, s45
	s_cselect_b32 s66, s24, s44
	s_ashr_i32 s11, s10, 31
	s_lshl_b64 s[30:31], s[10:11], 19
	s_add_u32 s30, s52, s30
	s_addc_u32 s31, s53, s31
	s_and_b64 s[48:49], s[4:5], exec
	s_cselect_b32 s11, s31, s47
	s_cselect_b32 s67, s30, s46
	s_add_u32 s44, s44, 0x40080
	s_addc_u32 s45, s45, 0
	s_add_u32 s68, s46, 0x100
	s_addc_u32 s69, s47, 0
	s_mov_b32 s70, -2
	ds_read_b128 v[140:143], v147
	ds_read_b128 v[150:153], v147 offset:1024
	ds_read_b128 v[154:157], v147 offset:2048
	ds_read_b128 v[158:161], v147 offset:3072
	ds_read_b128 v[162:165], v148
	ds_read_b128 v[166:169], v148 offset:1024
	ds_read_b128 v[170:173], v148 offset:2048
	ds_read_b128 v[174:177], v148 offset:3072
	s_add_u32 s18, s44, 0xfffc0080
	s_addc_u32 s19, s45, -1
	s_cmp_eq_u32 s70, 12
	s_cselect_b32 s49, s13, s19
	s_cselect_b32 s48, s66, s18
	s_cselect_b32 s47, s11, s69
	s_cselect_b32 s46, s67, s68
	v_lshl_add_u64 v[178:179], s[44:45], 0, v[132:133]
	s_add_i32 m0, s37, 0xc000
	ds_read_b128 v[184:187], v149
	ds_read_b128 v[188:191], v149 offset:1024
	ds_read_b128 v[192:195], v149 offset:2048
	ds_read_b128 v[196:199], v149 offset:3072
	ds_read_b128 v[200:203], v149 offset:4096
	ds_read_b128 v[204:207], v149 offset:5120
	ds_read_b128 v[208:211], v149 offset:6144
	ds_read_b128 v[212:215], v149 offset:7168
	global_load_lds_dwordx4 v[178:179], off
	v_lshl_add_u64 v[178:179], s[44:45], 0, v[134:135]
	s_add_i32 m0, s37, 0xe000
	s_nop 0
	global_load_lds_dwordx4 v[178:179], off
	s_waitcnt vmcnt(24)
	s_waitcnt lgkmcnt(0)
	s_barrier
	s_setprio 1
	s_waitcnt lgkmcnt(0)
	v_mfma_f32_16x16x32_bf16 v[124:127], v[140:143], v[184:187], 0
	v_mfma_f32_16x16x32_bf16 v[124:127], v[150:153], v[188:191], v[124:127]
	v_mfma_f32_16x16x32_bf16 v[120:123], v[154:157], v[184:187], 0
	v_mfma_f32_16x16x32_bf16 v[120:123], v[158:161], v[188:191], v[120:123]
	v_mfma_f32_16x16x32_bf16 v[108:111], v[140:143], v[192:195], 0
	v_mfma_f32_16x16x32_bf16 v[108:111], v[150:153], v[196:199], v[108:111]
	v_mfma_f32_16x16x32_bf16 v[104:107], v[154:157], v[192:195], 0
	v_mfma_f32_16x16x32_bf16 v[104:107], v[158:161], v[196:199], v[104:107]
	v_mfma_f32_16x16x32_bf16 v[92:95], v[140:143], v[200:203], 0
	v_mfma_f32_16x16x32_bf16 v[92:95], v[150:153], v[204:207], v[92:95]
	v_mfma_f32_16x16x32_bf16 v[88:91], v[154:157], v[200:203], 0
	v_mfma_f32_16x16x32_bf16 v[88:91], v[158:161], v[204:207], v[88:91]
	v_mfma_f32_16x16x32_bf16 v[76:79], v[140:143], v[208:211], 0
	v_mfma_f32_16x16x32_bf16 v[76:79], v[150:153], v[212:215], v[76:79]
	v_mfma_f32_16x16x32_bf16 v[72:75], v[154:157], v[208:211], 0
	v_mfma_f32_16x16x32_bf16 v[72:75], v[158:161], v[212:215], v[72:75]
	v_mfma_f32_16x16x32_bf16 v[116:119], v[162:165], v[184:187], 0
	v_mfma_f32_16x16x32_bf16 v[116:119], v[166:169], v[188:191], v[116:119]
	v_mfma_f32_16x16x32_bf16 v[112:115], v[170:173], v[184:187], 0
	v_mfma_f32_16x16x32_bf16 v[112:115], v[174:177], v[188:191], v[112:115]
	v_mfma_f32_16x16x32_bf16 v[100:103], v[162:165], v[192:195], 0
	v_mfma_f32_16x16x32_bf16 v[100:103], v[166:169], v[196:199], v[100:103]
	v_mfma_f32_16x16x32_bf16 v[96:99], v[170:173], v[192:195], 0
	v_mfma_f32_16x16x32_bf16 v[96:99], v[174:177], v[196:199], v[96:99]
	v_mfma_f32_16x16x32_bf16 v[84:87], v[162:165], v[200:203], 0
	v_mfma_f32_16x16x32_bf16 v[84:87], v[166:169], v[204:207], v[84:87]
	v_mfma_f32_16x16x32_bf16 v[80:83], v[170:173], v[200:203], 0
	v_mfma_f32_16x16x32_bf16 v[80:83], v[174:177], v[204:207], v[80:83]
	v_mfma_f32_16x16x32_bf16 v[68:71], v[162:165], v[208:211], 0
	v_mfma_f32_16x16x32_bf16 v[68:71], v[166:169], v[212:215], v[68:71]
	v_mfma_f32_16x16x32_bf16 v[64:67], v[170:173], v[208:211], 0
	v_mfma_f32_16x16x32_bf16 v[64:67], v[174:177], v[212:215], v[64:67]
	s_setprio 0
	s_barrier
	s_add_i32 s18, s62, s54
	v_lshl_add_u64 v[178:179], s[46:47], 0, v[130:131]
	s_mov_b32 m0, s18
	ds_read_b128 v[184:187], v149 offset:16384
	ds_read_b128 v[188:191], v149 offset:17408
	ds_read_b128 v[192:195], v149 offset:18432
	ds_read_b128 v[196:199], v149 offset:19456
	ds_read_b128 v[200:203], v149 offset:20480
	ds_read_b128 v[204:207], v149 offset:21504
	ds_read_b128 v[208:211], v149 offset:22528
	ds_read_b128 v[212:215], v149 offset:23552
	global_load_lds_dwordx4 v[178:179], off
	s_add_i32 m0, s18, 0x2000
	s_add_u32 s72, s46, 0x40000
	v_lshl_add_u64 v[216:217], s[46:47], 0, v[128:129]
	s_addc_u32 s73, s47, 0
	s_add_i32 s18, s63, s54
	global_load_lds_dwordx4 v[216:217], off
	v_lshl_add_u64 v[218:219], s[72:73], 0, v[130:131]
	s_mov_b32 m0, s18
	v_lshl_add_u64 v[220:221], s[48:49], 0, v[128:129]
	global_load_lds_dwordx4 v[218:219], off
	v_lshl_add_u64 v[218:219], s[72:73], 0, v[128:129]
	s_add_i32 m0, s18, 0x2000
	s_nop 0
	global_load_lds_dwordx4 v[218:219], off
	v_lshl_add_u64 v[218:219], s[48:49], 0, v[130:131]
	s_mov_b32 m0, s37
	s_nop 0
	global_load_lds_dwordx4 v[218:219], off
	s_mov_b32 m0, s56
	s_nop 0
	global_load_lds_dwordx4 v[220:221], off
	s_cmp_eq_u32 s98, 0
	s_cbranch_scc1 .Lpw8_0
	s_waitcnt vmcnt(24)
	s_branch .Lpwj_0

.Lpwj_0:
	s_waitcnt lgkmcnt(0)
	s_barrier
	s_setprio 1
	s_waitcnt lgkmcnt(0)
	v_mfma_f32_16x16x32_bf16 v[60:63], v[140:143], v[184:187], 0
	v_mfma_f32_16x16x32_bf16 v[60:63], v[150:153], v[188:191], v[60:63]
	v_mfma_f32_16x16x32_bf16 v[56:59], v[154:157], v[184:187], 0
	v_mfma_f32_16x16x32_bf16 v[56:59], v[158:161], v[188:191], v[56:59]
	v_mfma_f32_16x16x32_bf16 v[44:47], v[140:143], v[192:195], 0
	v_mfma_f32_16x16x32_bf16 v[44:47], v[150:153], v[196:199], v[44:47]
	v_mfma_f32_16x16x32_bf16 v[40:43], v[154:157], v[192:195], 0
	v_mfma_f32_16x16x32_bf16 v[40:43], v[158:161], v[196:199], v[40:43]
	v_mfma_f32_16x16x32_bf16 v[28:31], v[140:143], v[200:203], 0
	v_mfma_f32_16x16x32_bf16 v[28:31], v[150:153], v[204:207], v[28:31]
	v_mfma_f32_16x16x32_bf16 v[24:27], v[154:157], v[200:203], 0
	v_mfma_f32_16x16x32_bf16 v[24:27], v[158:161], v[204:207], v[24:27]
	v_mfma_f32_16x16x32_bf16 v[12:15], v[140:143], v[208:211], 0
	v_mfma_f32_16x16x32_bf16 v[12:15], v[150:153], v[212:215], v[12:15]
	v_mfma_f32_16x16x32_bf16 v[8:11], v[154:157], v[208:211], 0
	v_mfma_f32_16x16x32_bf16 v[8:11], v[158:161], v[212:215], v[8:11]
	v_mfma_f32_16x16x32_bf16 v[52:55], v[162:165], v[184:187], 0
	v_mfma_f32_16x16x32_bf16 v[52:55], v[166:169], v[188:191], v[52:55]
	v_mfma_f32_16x16x32_bf16 v[48:51], v[170:173], v[184:187], 0
	v_mfma_f32_16x16x32_bf16 v[48:51], v[174:177], v[188:191], v[48:51]
	v_mfma_f32_16x16x32_bf16 v[36:39], v[162:165], v[192:195], 0
	v_mfma_f32_16x16x32_bf16 v[36:39], v[166:169], v[196:199], v[36:39]
	v_mfma_f32_16x16x32_bf16 v[32:35], v[170:173], v[192:195], 0
	v_mfma_f32_16x16x32_bf16 v[32:35], v[174:177], v[196:199], v[32:35]
	v_mfma_f32_16x16x32_bf16 v[20:23], v[162:165], v[200:203], 0
	v_mfma_f32_16x16x32_bf16 v[20:23], v[166:169], v[204:207], v[20:23]
	v_mfma_f32_16x16x32_bf16 v[16:19], v[170:173], v[200:203], 0
	v_mfma_f32_16x16x32_bf16 v[16:19], v[174:177], v[204:207], v[16:19]
	v_mfma_f32_16x16x32_bf16 v[4:7], v[162:165], v[208:211], 0
	v_mfma_f32_16x16x32_bf16 v[4:7], v[166:169], v[212:215], v[4:7]
	v_mfma_f32_16x16x32_bf16 v[0:3], v[170:173], v[208:211], 0
	v_mfma_f32_16x16x32_bf16 v[0:3], v[174:177], v[212:215], v[0:3]
	s_setprio 0
	s_barrier
	s_branch .Lmid_gemm0

.LBB0_263:
	s_add_u32 s84, s54, 0x100
	s_addc_u32 s85, s55, 0
	s_mov_b32 s86, -2
	ds_read_b128 v[152:155], v149
	ds_read_b128 v[156:159], v149 offset:1024
	ds_read_b128 v[160:163], v149 offset:2048
	ds_read_b128 v[164:167], v149 offset:3072
	ds_read_b128 v[168:171], v150
	ds_read_b128 v[172:175], v150 offset:1024
	ds_read_b128 v[176:179], v150 offset:2048
	ds_read_b128 v[184:187], v150 offset:3072
	s_add_u32 s54, s52, 0x100
	s_addc_u32 s55, s53, 0
	s_cmp_eq_u32 s86, 40
	s_cselect_b32 s59, s7, s55
	s_cselect_b32 s58, s6, s54
	s_cselect_b32 s57, s49, s85
	s_cselect_b32 s56, s48, s84
	v_lshl_add_u64 v[144:145], s[52:53], 0, v[136:137]
	s_add_i32 m0, s63, 0xc000
	ds_read_b128 v[188:191], v151
	ds_read_b128 v[192:195], v151 offset:1024
	ds_read_b128 v[196:199], v151 offset:2048
	ds_read_b128 v[200:203], v151 offset:3072
	ds_read_b128 v[204:207], v151 offset:4096
	ds_read_b128 v[208:211], v151 offset:5120
	ds_read_b128 v[212:215], v151 offset:6144
	ds_read_b128 v[216:219], v151 offset:7168
	global_load_lds_dwordx4 v[144:145], off
	v_lshl_add_u64 v[144:145], s[52:53], 0, v[138:139]
	s_add_i32 m0, s63, 0xe000
	s_nop 0
	global_load_lds_dwordx4 v[144:145], off
	s_waitcnt vmcnt(24)
	s_waitcnt lgkmcnt(0)
	s_barrier
	s_setprio 1
	s_waitcnt lgkmcnt(0)
	v_mfma_f32_16x16x32_bf16 v[124:127], v[152:155], v[188:191], 0
	v_mfma_f32_16x16x32_bf16 v[124:127], v[156:159], v[192:195], v[124:127]
	v_mfma_f32_16x16x32_bf16 v[120:123], v[160:163], v[188:191], 0
	v_mfma_f32_16x16x32_bf16 v[120:123], v[164:167], v[192:195], v[120:123]
	v_mfma_f32_16x16x32_bf16 v[116:119], v[152:155], v[196:199], 0
	v_mfma_f32_16x16x32_bf16 v[116:119], v[156:159], v[200:203], v[116:119]
	v_mfma_f32_16x16x32_bf16 v[108:111], v[160:163], v[196:199], 0
	v_mfma_f32_16x16x32_bf16 v[108:111], v[164:167], v[200:203], v[108:111]
	v_mfma_f32_16x16x32_bf16 v[100:103], v[152:155], v[204:207], 0
	v_mfma_f32_16x16x32_bf16 v[100:103], v[156:159], v[208:211], v[100:103]
	v_mfma_f32_16x16x32_bf16 v[92:95], v[160:163], v[204:207], 0
	v_mfma_f32_16x16x32_bf16 v[92:95], v[164:167], v[208:211], v[92:95]
	v_mfma_f32_16x16x32_bf16 v[84:87], v[152:155], v[212:215], 0
	v_mfma_f32_16x16x32_bf16 v[84:87], v[156:159], v[216:219], v[84:87]
	v_mfma_f32_16x16x32_bf16 v[76:79], v[160:163], v[212:215], 0
	v_mfma_f32_16x16x32_bf16 v[76:79], v[164:167], v[216:219], v[76:79]
	v_mfma_f32_16x16x32_bf16 v[112:115], v[168:171], v[188:191], 0
	v_mfma_f32_16x16x32_bf16 v[112:115], v[172:175], v[192:195], v[112:115]
	v_mfma_f32_16x16x32_bf16 v[104:107], v[176:179], v[188:191], 0
	v_mfma_f32_16x16x32_bf16 v[104:107], v[184:187], v[192:195], v[104:107]
	v_mfma_f32_16x16x32_bf16 v[96:99], v[168:171], v[196:199], 0
	v_mfma_f32_16x16x32_bf16 v[96:99], v[172:175], v[200:203], v[96:99]
	v_mfma_f32_16x16x32_bf16 v[88:91], v[176:179], v[196:199], 0
	v_mfma_f32_16x16x32_bf16 v[88:91], v[184:187], v[200:203], v[88:91]
	v_mfma_f32_16x16x32_bf16 v[80:83], v[168:171], v[204:207], 0
	v_mfma_f32_16x16x32_bf16 v[80:83], v[172:175], v[208:211], v[80:83]
	v_mfma_f32_16x16x32_bf16 v[72:75], v[176:179], v[204:207], 0
	v_mfma_f32_16x16x32_bf16 v[72:75], v[184:187], v[208:211], v[72:75]
	v_mfma_f32_16x16x32_bf16 v[68:71], v[168:171], v[212:215], 0
	v_mfma_f32_16x16x32_bf16 v[68:71], v[172:175], v[216:219], v[68:71]
	v_mfma_f32_16x16x32_bf16 v[64:67], v[176:179], v[212:215], 0
	v_mfma_f32_16x16x32_bf16 v[64:67], v[184:187], v[216:219], v[64:67]
	s_setprio 0
	s_barrier
	s_add_i32 s18, s70, s62
	v_lshl_add_u64 v[144:145], s[56:57], 0, v[130:131]
	s_mov_b32 m0, s18
	ds_read_b128 v[188:191], v151 offset:16384
	ds_read_b128 v[192:195], v151 offset:17408
	ds_read_b128 v[196:199], v151 offset:18432
	ds_read_b128 v[200:203], v151 offset:19456
	ds_read_b128 v[204:207], v151 offset:20480
	ds_read_b128 v[208:211], v151 offset:21504
	ds_read_b128 v[212:215], v151 offset:22528
	ds_read_b128 v[216:219], v151 offset:23552
	global_load_lds_dwordx4 v[144:145], off
	s_add_i32 m0, s18, 0x2000
	s_add_u32 s52, s56, 0xb0000
	v_lshl_add_u64 v[220:221], s[56:57], 0, v[134:135]
	s_addc_u32 s53, s57, 0
	s_add_i32 s18, s71, s62
	global_load_lds_dwordx4 v[220:221], off
	v_lshl_add_u64 v[222:223], s[52:53], 0, v[130:131]
	s_mov_b32 m0, s18
	v_lshl_add_u64 v[224:225], s[58:59], 0, v[132:133]
	global_load_lds_dwordx4 v[222:223], off
	v_lshl_add_u64 v[222:223], s[52:53], 0, v[134:135]
	s_add_i32 m0, s18, 0x2000
	s_nop 0
	global_load_lds_dwordx4 v[222:223], off
	v_lshl_add_u64 v[222:223], s[58:59], 0, v[128:129]
	s_mov_b32 m0, s63
	s_nop 0
	global_load_lds_dwordx4 v[222:223], off
	s_mov_b32 m0, s64
	s_nop 0
	global_load_lds_dwordx4 v[224:225], off
	s_cmp_eq_u32 s98, 0
	s_cbranch_scc1 .Lpw8_1
	s_waitcnt vmcnt(24)
	s_branch .Lpwj_1

.Lpwj_1:
	s_waitcnt lgkmcnt(0)
	s_barrier
	s_setprio 1
	s_waitcnt lgkmcnt(0)
	v_mfma_f32_16x16x32_bf16 v[60:63], v[152:155], v[188:191], 0
	v_mfma_f32_16x16x32_bf16 v[60:63], v[156:159], v[192:195], v[60:63]
	v_mfma_f32_16x16x32_bf16 v[56:59], v[160:163], v[188:191], 0
	v_mfma_f32_16x16x32_bf16 v[56:59], v[164:167], v[192:195], v[56:59]
	v_mfma_f32_16x16x32_bf16 v[52:55], v[152:155], v[196:199], 0
	v_mfma_f32_16x16x32_bf16 v[52:55], v[156:159], v[200:203], v[52:55]
	v_mfma_f32_16x16x32_bf16 v[44:47], v[160:163], v[196:199], 0
	v_mfma_f32_16x16x32_bf16 v[44:47], v[164:167], v[200:203], v[44:47]
	v_mfma_f32_16x16x32_bf16 v[36:39], v[152:155], v[204:207], 0
	v_mfma_f32_16x16x32_bf16 v[36:39], v[156:159], v[208:211], v[36:39]
	v_mfma_f32_16x16x32_bf16 v[28:31], v[160:163], v[204:207], 0
	v_mfma_f32_16x16x32_bf16 v[28:31], v[164:167], v[208:211], v[28:31]
	v_mfma_f32_16x16x32_bf16 v[20:23], v[152:155], v[212:215], 0
	v_mfma_f32_16x16x32_bf16 v[20:23], v[156:159], v[216:219], v[20:23]
	v_mfma_f32_16x16x32_bf16 v[12:15], v[160:163], v[212:215], 0
	v_mfma_f32_16x16x32_bf16 v[12:15], v[164:167], v[216:219], v[12:15]
	v_mfma_f32_16x16x32_bf16 v[48:51], v[168:171], v[188:191], 0
	v_mfma_f32_16x16x32_bf16 v[48:51], v[172:175], v[192:195], v[48:51]
	v_mfma_f32_16x16x32_bf16 v[40:43], v[176:179], v[188:191], 0
	v_mfma_f32_16x16x32_bf16 v[40:43], v[184:187], v[192:195], v[40:43]
	v_mfma_f32_16x16x32_bf16 v[32:35], v[168:171], v[196:199], 0
	v_mfma_f32_16x16x32_bf16 v[32:35], v[172:175], v[200:203], v[32:35]
	v_mfma_f32_16x16x32_bf16 v[24:27], v[176:179], v[196:199], 0
	v_mfma_f32_16x16x32_bf16 v[24:27], v[184:187], v[200:203], v[24:27]
	v_mfma_f32_16x16x32_bf16 v[16:19], v[168:171], v[204:207], 0
	v_mfma_f32_16x16x32_bf16 v[16:19], v[172:175], v[208:211], v[16:19]
	v_mfma_f32_16x16x32_bf16 v[8:11], v[176:179], v[204:207], 0
	v_mfma_f32_16x16x32_bf16 v[8:11], v[184:187], v[208:211], v[8:11]
	v_mfma_f32_16x16x32_bf16 v[4:7], v[168:171], v[212:215], 0
	v_mfma_f32_16x16x32_bf16 v[4:7], v[172:175], v[216:219], v[4:7]
	v_mfma_f32_16x16x32_bf16 v[0:3], v[176:179], v[212:215], 0
	v_mfma_f32_16x16x32_bf16 v[0:3], v[184:187], v[216:219], v[0:3]
	s_setprio 0
	s_barrier
	s_branch .Lmid_gemm1

.LBB0_386:
	s_ashr_i32 s49, s48, 31
	s_lshl_b64 s[52:53], s[48:49], 19
	s_add_u32 s52, s80, s52
	s_addc_u32 s53, s81, s53
	s_and_b64 s[54:55], s[4:5], exec
	s_cselect_b32 s49, s53, s59
	s_cselect_b32 s82, s52, s58
	s_ashr_i32 s47, s46, 31
	s_lshl_b64 s[54:55], s[46:47], 19
	s_add_u32 s54, s64, s54
	s_addc_u32 s55, s65, s55
	s_and_b64 s[62:63], s[4:5], exec
	s_cselect_b32 s47, s55, s61
	s_cselect_b32 s83, s54, s60
	s_add_u32 s58, s58, 0x40080
	s_addc_u32 s59, s59, 0
	s_add_u32 s84, s60, 0x100
	s_addc_u32 s85, s61, 0
	s_mov_b32 s86, -2
	ds_read_b128 v[152:155], v148
	ds_read_b128 v[156:159], v148 offset:1024
	ds_read_b128 v[160:163], v148 offset:2048
	ds_read_b128 v[164:167], v148 offset:3072
	ds_read_b128 v[168:171], v149
	ds_read_b128 v[172:175], v149 offset:1024
	ds_read_b128 v[176:179], v149 offset:2048
	ds_read_b128 v[184:187], v149 offset:3072
	s_add_u32 s18, s58, 0xfffc0080
	s_addc_u32 s19, s59, -1
	s_cmp_eq_u32 s86, 12
	s_cselect_b32 s63, s49, s19
	s_cselect_b32 s62, s82, s18
	s_cselect_b32 s61, s47, s85
	s_cselect_b32 s60, s83, s84
	v_lshl_add_u64 v[220:221], s[58:59], 0, v[138:139]
	s_add_i32 m0, s68, 0xc000
	ds_read_b128 v[188:191], v150
	ds_read_b128 v[192:195], v150 offset:1024
	ds_read_b128 v[196:199], v150 offset:2048
	ds_read_b128 v[200:203], v150 offset:3072
	ds_read_b128 v[204:207], v150 offset:4096
	ds_read_b128 v[208:211], v150 offset:5120
	ds_read_b128 v[212:215], v150 offset:6144
	ds_read_b128 v[216:219], v150 offset:7168
	global_load_lds_dwordx4 v[220:221], off
	v_lshl_add_u64 v[220:221], s[58:59], 0, v[140:141]
	s_add_i32 m0, s68, 0xe000
	s_nop 0
	global_load_lds_dwordx4 v[220:221], off
	s_waitcnt vmcnt(24)
	s_waitcnt lgkmcnt(0)
	s_barrier
	s_setprio 1
	s_waitcnt lgkmcnt(0)
	v_mfma_f32_16x16x32_bf16 v[124:127], v[152:155], v[188:191], 0
	v_mfma_f32_16x16x32_bf16 v[124:127], v[156:159], v[192:195], v[124:127]
	v_mfma_f32_16x16x32_bf16 v[120:123], v[160:163], v[188:191], 0
	v_mfma_f32_16x16x32_bf16 v[120:123], v[164:167], v[192:195], v[120:123]
	v_mfma_f32_16x16x32_bf16 v[116:119], v[152:155], v[196:199], 0
	v_mfma_f32_16x16x32_bf16 v[116:119], v[156:159], v[200:203], v[116:119]
	v_mfma_f32_16x16x32_bf16 v[112:115], v[160:163], v[196:199], 0
	v_mfma_f32_16x16x32_bf16 v[112:115], v[164:167], v[200:203], v[112:115]
	v_mfma_f32_16x16x32_bf16 v[108:111], v[152:155], v[204:207], 0
	v_mfma_f32_16x16x32_bf16 v[108:111], v[156:159], v[208:211], v[108:111]
	v_mfma_f32_16x16x32_bf16 v[104:107], v[160:163], v[204:207], 0
	v_mfma_f32_16x16x32_bf16 v[104:107], v[164:167], v[208:211], v[104:107]
	v_mfma_f32_16x16x32_bf16 v[100:103], v[152:155], v[212:215], 0
	v_mfma_f32_16x16x32_bf16 v[100:103], v[156:159], v[216:219], v[100:103]
	v_mfma_f32_16x16x32_bf16 v[96:99], v[160:163], v[212:215], 0
	v_mfma_f32_16x16x32_bf16 v[96:99], v[164:167], v[216:219], v[96:99]
	v_mfma_f32_16x16x32_bf16 v[68:71], v[168:171], v[188:191], 0
	v_mfma_f32_16x16x32_bf16 v[68:71], v[172:175], v[192:195], v[68:71]
	v_mfma_f32_16x16x32_bf16 v[64:67], v[176:179], v[188:191], 0
	v_mfma_f32_16x16x32_bf16 v[64:67], v[184:187], v[192:195], v[64:67]
	v_mfma_f32_16x16x32_bf16 v[52:55], v[168:171], v[196:199], 0
	v_mfma_f32_16x16x32_bf16 v[52:55], v[172:175], v[200:203], v[52:55]
	v_mfma_f32_16x16x32_bf16 v[48:51], v[176:179], v[196:199], 0
	v_mfma_f32_16x16x32_bf16 v[48:51], v[184:187], v[200:203], v[48:51]
	v_mfma_f32_16x16x32_bf16 v[44:47], v[168:171], v[204:207], 0
	v_mfma_f32_16x16x32_bf16 v[44:47], v[172:175], v[208:211], v[44:47]
	v_mfma_f32_16x16x32_bf16 v[40:43], v[176:179], v[204:207], 0
	v_mfma_f32_16x16x32_bf16 v[40:43], v[184:187], v[208:211], v[40:43]
	v_mfma_f32_16x16x32_bf16 v[36:39], v[168:171], v[212:215], 0
	v_mfma_f32_16x16x32_bf16 v[36:39], v[172:175], v[216:219], v[36:39]
	v_mfma_f32_16x16x32_bf16 v[32:35], v[176:179], v[212:215], 0
	v_mfma_f32_16x16x32_bf16 v[32:35], v[184:187], v[216:219], v[32:35]
	s_setprio 0
	s_barrier
	s_add_i32 s18, s76, s66
	v_lshl_add_u64 v[220:221], s[60:61], 0, v[132:133]
	s_mov_b32 m0, s18
	ds_read_b128 v[188:191], v150 offset:16384
	ds_read_b128 v[192:195], v150 offset:17408
	ds_read_b128 v[196:199], v150 offset:18432
	ds_read_b128 v[200:203], v150 offset:19456
	ds_read_b128 v[204:207], v150 offset:20480
	ds_read_b128 v[208:211], v150 offset:21504
	ds_read_b128 v[212:215], v150 offset:22528
	ds_read_b128 v[216:219], v150 offset:23552
	global_load_lds_dwordx4 v[220:221], off
	s_add_i32 m0, s18, 0x2000
	s_add_u32 s88, s60, 0x40000
	v_lshl_add_u64 v[222:223], s[60:61], 0, v[128:129]
	s_addc_u32 s89, s61, 0
	s_add_i32 s18, s77, s66
	global_load_lds_dwordx4 v[222:223], off
	v_lshl_add_u64 v[224:225], s[88:89], 0, v[132:133]
	s_mov_b32 m0, s18
	v_lshl_add_u64 v[226:227], s[62:63], 0, v[130:131]
	global_load_lds_dwordx4 v[224:225], off
	v_lshl_add_u64 v[224:225], s[88:89], 0, v[128:129]
	s_add_i32 m0, s18, 0x2000
	s_nop 0
	global_load_lds_dwordx4 v[224:225], off
	v_lshl_add_u64 v[224:225], s[62:63], 0, v[134:135]
	s_mov_b32 m0, s68
	s_nop 0
	global_load_lds_dwordx4 v[224:225], off
	s_mov_b32 m0, s69
	s_nop 0
	global_load_lds_dwordx4 v[226:227], off
	s_cmp_eq_u32 s98, 0
	s_cbranch_scc1 .Lpw8_2
	s_waitcnt vmcnt(24)
	s_branch .Lpwj_2

.Lpwj_2:
	s_waitcnt lgkmcnt(0)
	s_barrier
	s_setprio 1
	s_waitcnt lgkmcnt(0)
	v_mfma_f32_16x16x32_bf16 v[92:95], v[152:155], v[188:191], 0
	v_mfma_f32_16x16x32_bf16 v[92:95], v[156:159], v[192:195], v[92:95]
	v_mfma_f32_16x16x32_bf16 v[88:91], v[160:163], v[188:191], 0
	v_mfma_f32_16x16x32_bf16 v[88:91], v[164:167], v[192:195], v[88:91]
	v_mfma_f32_16x16x32_bf16 v[84:87], v[152:155], v[196:199], 0
	v_mfma_f32_16x16x32_bf16 v[84:87], v[156:159], v[200:203], v[84:87]
	v_mfma_f32_16x16x32_bf16 v[80:83], v[160:163], v[196:199], 0
	v_mfma_f32_16x16x32_bf16 v[80:83], v[164:167], v[200:203], v[80:83]
	v_mfma_f32_16x16x32_bf16 v[76:79], v[152:155], v[204:207], 0
	v_mfma_f32_16x16x32_bf16 v[76:79], v[156:159], v[208:211], v[76:79]
	v_mfma_f32_16x16x32_bf16 v[72:75], v[160:163], v[204:207], 0
	v_mfma_f32_16x16x32_bf16 v[72:75], v[164:167], v[208:211], v[72:75]
	v_mfma_f32_16x16x32_bf16 v[60:63], v[152:155], v[212:215], 0
	v_mfma_f32_16x16x32_bf16 v[60:63], v[156:159], v[216:219], v[60:63]
	v_mfma_f32_16x16x32_bf16 v[56:59], v[160:163], v[212:215], 0
	v_mfma_f32_16x16x32_bf16 v[56:59], v[164:167], v[216:219], v[56:59]
	v_mfma_f32_16x16x32_bf16 v[28:31], v[168:171], v[188:191], 0
	v_mfma_f32_16x16x32_bf16 v[28:31], v[172:175], v[192:195], v[28:31]
	v_mfma_f32_16x16x32_bf16 v[24:27], v[176:179], v[188:191], 0
	v_mfma_f32_16x16x32_bf16 v[24:27], v[184:187], v[192:195], v[24:27]
	v_mfma_f32_16x16x32_bf16 v[20:23], v[168:171], v[196:199], 0
	v_mfma_f32_16x16x32_bf16 v[20:23], v[172:175], v[200:203], v[20:23]
	v_mfma_f32_16x16x32_bf16 v[16:19], v[176:179], v[196:199], 0
	v_mfma_f32_16x16x32_bf16 v[16:19], v[184:187], v[200:203], v[16:19]
	v_mfma_f32_16x16x32_bf16 v[12:15], v[168:171], v[204:207], 0
	v_mfma_f32_16x16x32_bf16 v[12:15], v[172:175], v[208:211], v[12:15]
	v_mfma_f32_16x16x32_bf16 v[8:11], v[176:179], v[204:207], 0
	v_mfma_f32_16x16x32_bf16 v[8:11], v[184:187], v[208:211], v[8:11]
	v_mfma_f32_16x16x32_bf16 v[4:7], v[168:171], v[212:215], 0
	v_mfma_f32_16x16x32_bf16 v[4:7], v[172:175], v[216:219], v[4:7]
	v_mfma_f32_16x16x32_bf16 v[0:3], v[176:179], v[212:215], 0
	v_mfma_f32_16x16x32_bf16 v[0:3], v[184:187], v[216:219], v[0:3]
	s_setprio 0
	s_barrier
	s_branch .Lmid_gemm2

.LBB0_600:
	s_ashr_i32 s49, s48, 31
	s_lshl_b64 s[18:19], s[48:49], 19
	s_add_u32 s52, s38, s18
	s_addc_u32 s53, s39, s19
	s_and_b64 s[18:19], s[4:5], exec
	s_cselect_b32 s49, s53, s59
	s_cselect_b32 s84, s52, s58
	s_ashr_i32 s47, s46, 31
	s_lshl_b64 s[18:19], s[46:47], 19
	s_add_u32 s54, s64, s18
	s_addc_u32 s55, s65, s19
	s_and_b64 s[18:19], s[4:5], exec
	s_cselect_b32 s47, s55, s61
	s_cselect_b32 s85, s54, s60
	s_add_u32 s58, s58, 0x40080
	s_addc_u32 s59, s59, 0
	s_add_u32 s86, s60, 0x100
	s_addc_u32 s87, s61, 0
	s_mov_b32 s88, -2
	ds_read_b128 v[152:155], v149
	ds_read_b128 v[156:159], v149 offset:1024
	ds_read_b128 v[160:163], v149 offset:2048
	ds_read_b128 v[164:167], v149 offset:3072
	ds_read_b128 v[168:171], v150
	ds_read_b128 v[172:175], v150 offset:1024
	ds_read_b128 v[176:179], v150 offset:2048
	ds_read_b128 v[184:187], v150 offset:3072
	s_add_u32 s18, s58, 0xfffc0080
	s_addc_u32 s19, s59, -1
	s_cmp_eq_u32 s88, 12
	s_cselect_b32 s63, s49, s19
	s_cselect_b32 s62, s84, s18
	s_cselect_b32 s61, s47, s87
	s_cselect_b32 s60, s85, s86
	v_lshl_add_u64 v[144:145], s[58:59], 0, v[136:137]
	s_add_i32 m0, s57, 0xc000
	ds_read_b128 v[188:191], v151
	ds_read_b128 v[192:195], v151 offset:1024
	ds_read_b128 v[196:199], v151 offset:2048
	ds_read_b128 v[200:203], v151 offset:3072
	ds_read_b128 v[204:207], v151 offset:4096
	ds_read_b128 v[208:211], v151 offset:5120
	ds_read_b128 v[212:215], v151 offset:6144
	ds_read_b128 v[216:219], v151 offset:7168
	global_load_lds_dwordx4 v[144:145], off
	v_lshl_add_u64 v[144:145], s[58:59], 0, v[138:139]
	s_add_i32 m0, s57, 0xe000
	s_nop 0
	global_load_lds_dwordx4 v[144:145], off
	s_waitcnt vmcnt(24)
	s_waitcnt lgkmcnt(0)
	s_barrier
	s_setprio 1
	s_waitcnt lgkmcnt(0)
	v_mfma_f32_16x16x32_bf16 v[124:127], v[152:155], v[188:191], 0
	v_mfma_f32_16x16x32_bf16 v[124:127], v[156:159], v[192:195], v[124:127]
	v_mfma_f32_16x16x32_bf16 v[120:123], v[160:163], v[188:191], 0
	v_mfma_f32_16x16x32_bf16 v[120:123], v[164:167], v[192:195], v[120:123]
	v_mfma_f32_16x16x32_bf16 v[116:119], v[152:155], v[196:199], 0
	v_mfma_f32_16x16x32_bf16 v[116:119], v[156:159], v[200:203], v[116:119]
	v_mfma_f32_16x16x32_bf16 v[108:111], v[160:163], v[196:199], 0
	v_mfma_f32_16x16x32_bf16 v[108:111], v[164:167], v[200:203], v[108:111]
	v_mfma_f32_16x16x32_bf16 v[100:103], v[152:155], v[204:207], 0
	v_mfma_f32_16x16x32_bf16 v[100:103], v[156:159], v[208:211], v[100:103]
	v_mfma_f32_16x16x32_bf16 v[92:95], v[160:163], v[204:207], 0
	v_mfma_f32_16x16x32_bf16 v[92:95], v[164:167], v[208:211], v[92:95]
	v_mfma_f32_16x16x32_bf16 v[84:87], v[152:155], v[212:215], 0
	v_mfma_f32_16x16x32_bf16 v[84:87], v[156:159], v[216:219], v[84:87]
	v_mfma_f32_16x16x32_bf16 v[76:79], v[160:163], v[212:215], 0
	v_mfma_f32_16x16x32_bf16 v[76:79], v[164:167], v[216:219], v[76:79]
	v_mfma_f32_16x16x32_bf16 v[112:115], v[168:171], v[188:191], 0
	v_mfma_f32_16x16x32_bf16 v[112:115], v[172:175], v[192:195], v[112:115]
	v_mfma_f32_16x16x32_bf16 v[104:107], v[176:179], v[188:191], 0
	v_mfma_f32_16x16x32_bf16 v[104:107], v[184:187], v[192:195], v[104:107]
	v_mfma_f32_16x16x32_bf16 v[96:99], v[168:171], v[196:199], 0
	v_mfma_f32_16x16x32_bf16 v[96:99], v[172:175], v[200:203], v[96:99]
	v_mfma_f32_16x16x32_bf16 v[88:91], v[176:179], v[196:199], 0
	v_mfma_f32_16x16x32_bf16 v[88:91], v[184:187], v[200:203], v[88:91]
	v_mfma_f32_16x16x32_bf16 v[80:83], v[168:171], v[204:207], 0
	v_mfma_f32_16x16x32_bf16 v[80:83], v[172:175], v[208:211], v[80:83]
	v_mfma_f32_16x16x32_bf16 v[72:75], v[176:179], v[204:207], 0
	v_mfma_f32_16x16x32_bf16 v[72:75], v[184:187], v[208:211], v[72:75]
	v_mfma_f32_16x16x32_bf16 v[68:71], v[168:171], v[212:215], 0
	v_mfma_f32_16x16x32_bf16 v[68:71], v[172:175], v[216:219], v[68:71]
	v_mfma_f32_16x16x32_bf16 v[64:67], v[176:179], v[212:215], 0
	v_mfma_f32_16x16x32_bf16 v[64:67], v[184:187], v[216:219], v[64:67]
	s_setprio 0
	s_barrier
	s_add_i32 s18, s73, s66
	v_lshl_add_u64 v[144:145], s[60:61], 0, v[130:131]
	s_mov_b32 m0, s18
	ds_read_b128 v[188:191], v151 offset:16384
	ds_read_b128 v[192:195], v151 offset:17408
	ds_read_b128 v[196:199], v151 offset:18432
	ds_read_b128 v[200:203], v151 offset:19456
	ds_read_b128 v[204:207], v151 offset:20480
	ds_read_b128 v[208:211], v151 offset:21504
	ds_read_b128 v[212:215], v151 offset:22528
	ds_read_b128 v[216:219], v151 offset:23552
	global_load_lds_dwordx4 v[144:145], off
	s_add_i32 m0, s18, 0x2000
	s_add_u32 s18, s60, 0x40000
	v_lshl_add_u64 v[220:221], s[60:61], 0, v[134:135]
	s_addc_u32 s19, s61, 0
	s_add_i32 s79, s74, s66
	global_load_lds_dwordx4 v[220:221], off
	v_lshl_add_u64 v[222:223], s[18:19], 0, v[130:131]
	s_mov_b32 m0, s79
	v_lshl_add_u64 v[224:225], s[62:63], 0, v[132:133]
	global_load_lds_dwordx4 v[222:223], off
	v_lshl_add_u64 v[222:223], s[18:19], 0, v[134:135]
	s_add_i32 m0, s79, 0x2000
	s_nop 0
	global_load_lds_dwordx4 v[222:223], off
	v_lshl_add_u64 v[222:223], s[62:63], 0, v[128:129]
	s_mov_b32 m0, s57
	s_nop 0
	global_load_lds_dwordx4 v[222:223], off
	s_mov_b32 m0, s67
	s_nop 0
	global_load_lds_dwordx4 v[224:225], off
	s_cmp_eq_u32 s98, 0
	s_cbranch_scc1 .Lpw8_3
	s_waitcnt vmcnt(24)
	s_branch .Lpwj_3

.LBB0_723:
	s_ashr_i32 s31, s30, 31
	s_lshl_b64 s[36:37], s[30:31], 19
	s_add_u32 s36, s80, s36
	s_addc_u32 s37, s81, s37
	s_and_b64 s[44:45], s[10:11], exec
	s_cselect_b32 s31, s37, s49
	s_cselect_b32 s70, s36, s48
	s_ashr_i32 s19, s18, 31
	s_lshl_b64 s[44:45], s[18:19], 19
	s_add_u32 s44, s56, s44
	s_addc_u32 s45, s57, s45
	s_and_b64 s[54:55], s[10:11], exec
	s_cselect_b32 s19, s45, s53
	s_cselect_b32 s71, s44, s52
	s_add_u32 s48, s48, 0x40080
	s_addc_u32 s49, s49, 0
	s_add_u32 s72, s52, 0x100
	s_addc_u32 s73, s53, 0
	s_mov_b32 s74, -2
	ds_read_b128 v[140:143], v147
	ds_read_b128 v[150:153], v147 offset:1024
	ds_read_b128 v[154:157], v147 offset:2048
	ds_read_b128 v[158:161], v147 offset:3072
	ds_read_b128 v[162:165], v148
	ds_read_b128 v[166:169], v148 offset:1024
	ds_read_b128 v[170:173], v148 offset:2048
	ds_read_b128 v[174:177], v148 offset:3072
	s_add_u32 s52, s48, 0xfffc0080
	s_addc_u32 s53, s49, -1
	s_cmp_eq_u32 s74, 12
	s_cselect_b32 s55, s31, s53
	s_cselect_b32 s54, s70, s52
	s_cselect_b32 s53, s19, s73
	s_cselect_b32 s52, s71, s72
	v_lshl_add_u64 v[178:179], s[48:49], 0, v[132:133]
	s_add_i32 m0, s47, 0xc000
	ds_read_b128 v[184:187], v149
	ds_read_b128 v[188:191], v149 offset:1024
	ds_read_b128 v[192:195], v149 offset:2048
	ds_read_b128 v[196:199], v149 offset:3072
	ds_read_b128 v[200:203], v149 offset:4096
	ds_read_b128 v[204:207], v149 offset:5120
	ds_read_b128 v[208:211], v149 offset:6144
	ds_read_b128 v[212:215], v149 offset:7168
	global_load_lds_dwordx4 v[178:179], off
	v_lshl_add_u64 v[178:179], s[48:49], 0, v[134:135]
	s_add_i32 m0, s47, 0xe000
	s_nop 0
	global_load_lds_dwordx4 v[178:179], off
	s_waitcnt vmcnt(24)
	s_waitcnt lgkmcnt(0)
	s_barrier
	s_setprio 1
	s_waitcnt lgkmcnt(0)
	v_mfma_f32_16x16x32_bf16 v[124:127], v[140:143], v[184:187], 0
	v_mfma_f32_16x16x32_bf16 v[124:127], v[150:153], v[188:191], v[124:127]
	v_mfma_f32_16x16x32_bf16 v[120:123], v[154:157], v[184:187], 0
	v_mfma_f32_16x16x32_bf16 v[120:123], v[158:161], v[188:191], v[120:123]
	v_mfma_f32_16x16x32_bf16 v[108:111], v[140:143], v[192:195], 0
	v_mfma_f32_16x16x32_bf16 v[108:111], v[150:153], v[196:199], v[108:111]
	v_mfma_f32_16x16x32_bf16 v[104:107], v[154:157], v[192:195], 0
	v_mfma_f32_16x16x32_bf16 v[104:107], v[158:161], v[196:199], v[104:107]
	v_mfma_f32_16x16x32_bf16 v[92:95], v[140:143], v[200:203], 0
	v_mfma_f32_16x16x32_bf16 v[92:95], v[150:153], v[204:207], v[92:95]
	v_mfma_f32_16x16x32_bf16 v[88:91], v[154:157], v[200:203], 0
	v_mfma_f32_16x16x32_bf16 v[88:91], v[158:161], v[204:207], v[88:91]
	v_mfma_f32_16x16x32_bf16 v[76:79], v[140:143], v[208:211], 0
	v_mfma_f32_16x16x32_bf16 v[76:79], v[150:153], v[212:215], v[76:79]
	v_mfma_f32_16x16x32_bf16 v[72:75], v[154:157], v[208:211], 0
	v_mfma_f32_16x16x32_bf16 v[72:75], v[158:161], v[212:215], v[72:75]
	v_mfma_f32_16x16x32_bf16 v[116:119], v[162:165], v[184:187], 0
	v_mfma_f32_16x16x32_bf16 v[116:119], v[166:169], v[188:191], v[116:119]
	v_mfma_f32_16x16x32_bf16 v[112:115], v[170:173], v[184:187], 0
	v_mfma_f32_16x16x32_bf16 v[112:115], v[174:177], v[188:191], v[112:115]
	v_mfma_f32_16x16x32_bf16 v[100:103], v[162:165], v[192:195], 0
	v_mfma_f32_16x16x32_bf16 v[100:103], v[166:169], v[196:199], v[100:103]
	v_mfma_f32_16x16x32_bf16 v[96:99], v[170:173], v[192:195], 0
	v_mfma_f32_16x16x32_bf16 v[96:99], v[174:177], v[196:199], v[96:99]
	v_mfma_f32_16x16x32_bf16 v[84:87], v[162:165], v[200:203], 0
	v_mfma_f32_16x16x32_bf16 v[84:87], v[166:169], v[204:207], v[84:87]
	v_mfma_f32_16x16x32_bf16 v[80:83], v[170:173], v[200:203], 0
	v_mfma_f32_16x16x32_bf16 v[80:83], v[174:177], v[204:207], v[80:83]
	v_mfma_f32_16x16x32_bf16 v[68:71], v[162:165], v[208:211], 0
	v_mfma_f32_16x16x32_bf16 v[68:71], v[166:169], v[212:215], v[68:71]
	v_mfma_f32_16x16x32_bf16 v[64:67], v[170:173], v[208:211], 0
	v_mfma_f32_16x16x32_bf16 v[64:67], v[174:177], v[212:215], v[64:67]
	s_setprio 0
	s_barrier
	s_add_i32 s75, s66, s58
	v_lshl_add_u64 v[178:179], s[52:53], 0, v[130:131]
	s_mov_b32 m0, s75
	ds_read_b128 v[184:187], v149 offset:16384
	ds_read_b128 v[188:191], v149 offset:17408
	ds_read_b128 v[192:195], v149 offset:18432
	ds_read_b128 v[196:199], v149 offset:19456
	ds_read_b128 v[200:203], v149 offset:20480
	ds_read_b128 v[204:207], v149 offset:21504
	ds_read_b128 v[208:211], v149 offset:22528
	ds_read_b128 v[212:215], v149 offset:23552
	global_load_lds_dwordx4 v[178:179], off
	s_add_i32 m0, s75, 0x2000
	s_add_u32 s76, s52, 0x40000
	v_lshl_add_u64 v[216:217], s[52:53], 0, v[128:129]
	s_addc_u32 s77, s53, 0
	s_add_i32 s75, s67, s58
	global_load_lds_dwordx4 v[216:217], off
	v_lshl_add_u64 v[218:219], s[76:77], 0, v[130:131]
	s_mov_b32 m0, s75
	v_lshl_add_u64 v[220:221], s[54:55], 0, v[128:129]
	global_load_lds_dwordx4 v[218:219], off
	v_lshl_add_u64 v[218:219], s[76:77], 0, v[128:129]
	s_add_i32 m0, s75, 0x2000
	s_nop 0
	global_load_lds_dwordx4 v[218:219], off
	v_lshl_add_u64 v[218:219], s[54:55], 0, v[130:131]
	s_mov_b32 m0, s47
	s_nop 0
	global_load_lds_dwordx4 v[218:219], off
	s_mov_b32 m0, s60
	s_nop 0
	global_load_lds_dwordx4 v[220:221], off
	s_cmp_eq_u32 s98, 0
	s_cbranch_scc1 .Lpw8_4
	s_waitcnt vmcnt(24)
	s_branch .Lpwj_4

.LBB0_803:
	s_add_u32 s84, s54, 0x100
	s_addc_u32 s85, s55, 0
	s_mov_b32 s86, -2
	ds_read_b128 v[152:155], v149
	ds_read_b128 v[156:159], v149 offset:1024
	ds_read_b128 v[160:163], v149 offset:2048
	ds_read_b128 v[164:167], v149 offset:3072
	ds_read_b128 v[168:171], v150
	ds_read_b128 v[172:175], v150 offset:1024
	ds_read_b128 v[176:179], v150 offset:2048
	ds_read_b128 v[184:187], v150 offset:3072
	s_add_u32 s54, s52, 0x100
	s_addc_u32 s55, s53, 0
	s_cmp_eq_u32 s86, 40
	s_cselect_b32 s59, s13, s55
	s_cselect_b32 s58, s12, s54
	s_cselect_b32 s57, s49, s85
	s_cselect_b32 s56, s48, s84
	v_lshl_add_u64 v[144:145], s[52:53], 0, v[136:137]
	s_add_i32 m0, s63, 0xc000
	ds_read_b128 v[188:191], v151
	ds_read_b128 v[192:195], v151 offset:1024
	ds_read_b128 v[196:199], v151 offset:2048
	ds_read_b128 v[200:203], v151 offset:3072
	ds_read_b128 v[204:207], v151 offset:4096
	ds_read_b128 v[208:211], v151 offset:5120
	ds_read_b128 v[212:215], v151 offset:6144
	ds_read_b128 v[216:219], v151 offset:7168
	global_load_lds_dwordx4 v[144:145], off
	v_lshl_add_u64 v[144:145], s[52:53], 0, v[138:139]
	s_add_i32 m0, s63, 0xe000
	s_nop 0
	global_load_lds_dwordx4 v[144:145], off
	s_waitcnt vmcnt(24)
	s_waitcnt lgkmcnt(0)
	s_barrier
	s_setprio 1
	s_waitcnt lgkmcnt(0)
	v_mfma_f32_16x16x32_bf16 v[124:127], v[152:155], v[188:191], 0
	v_mfma_f32_16x16x32_bf16 v[124:127], v[156:159], v[192:195], v[124:127]
	v_mfma_f32_16x16x32_bf16 v[120:123], v[160:163], v[188:191], 0
	v_mfma_f32_16x16x32_bf16 v[120:123], v[164:167], v[192:195], v[120:123]
	v_mfma_f32_16x16x32_bf16 v[116:119], v[152:155], v[196:199], 0
	v_mfma_f32_16x16x32_bf16 v[116:119], v[156:159], v[200:203], v[116:119]
	v_mfma_f32_16x16x32_bf16 v[108:111], v[160:163], v[196:199], 0
	v_mfma_f32_16x16x32_bf16 v[108:111], v[164:167], v[200:203], v[108:111]
	v_mfma_f32_16x16x32_bf16 v[100:103], v[152:155], v[204:207], 0
	v_mfma_f32_16x16x32_bf16 v[100:103], v[156:159], v[208:211], v[100:103]
	v_mfma_f32_16x16x32_bf16 v[92:95], v[160:163], v[204:207], 0
	v_mfma_f32_16x16x32_bf16 v[92:95], v[164:167], v[208:211], v[92:95]
	v_mfma_f32_16x16x32_bf16 v[84:87], v[152:155], v[212:215], 0
	v_mfma_f32_16x16x32_bf16 v[84:87], v[156:159], v[216:219], v[84:87]
	v_mfma_f32_16x16x32_bf16 v[76:79], v[160:163], v[212:215], 0
	v_mfma_f32_16x16x32_bf16 v[76:79], v[164:167], v[216:219], v[76:79]
	v_mfma_f32_16x16x32_bf16 v[112:115], v[168:171], v[188:191], 0
	v_mfma_f32_16x16x32_bf16 v[112:115], v[172:175], v[192:195], v[112:115]
	v_mfma_f32_16x16x32_bf16 v[104:107], v[176:179], v[188:191], 0
	v_mfma_f32_16x16x32_bf16 v[104:107], v[184:187], v[192:195], v[104:107]
	v_mfma_f32_16x16x32_bf16 v[96:99], v[168:171], v[196:199], 0
	v_mfma_f32_16x16x32_bf16 v[96:99], v[172:175], v[200:203], v[96:99]
	v_mfma_f32_16x16x32_bf16 v[88:91], v[176:179], v[196:199], 0
	v_mfma_f32_16x16x32_bf16 v[88:91], v[184:187], v[200:203], v[88:91]
	v_mfma_f32_16x16x32_bf16 v[80:83], v[168:171], v[204:207], 0
	v_mfma_f32_16x16x32_bf16 v[80:83], v[172:175], v[208:211], v[80:83]
	v_mfma_f32_16x16x32_bf16 v[72:75], v[176:179], v[204:207], 0
	v_mfma_f32_16x16x32_bf16 v[72:75], v[184:187], v[208:211], v[72:75]
	v_mfma_f32_16x16x32_bf16 v[68:71], v[168:171], v[212:215], 0
	v_mfma_f32_16x16x32_bf16 v[68:71], v[172:175], v[216:219], v[68:71]
	v_mfma_f32_16x16x32_bf16 v[64:67], v[176:179], v[212:215], 0
	v_mfma_f32_16x16x32_bf16 v[64:67], v[184:187], v[216:219], v[64:67]
	s_setprio 0
	s_barrier
	s_add_i32 s52, s70, s62
	v_lshl_add_u64 v[144:145], s[56:57], 0, v[130:131]
	s_mov_b32 m0, s52
	ds_read_b128 v[188:191], v151 offset:16384
	ds_read_b128 v[192:195], v151 offset:17408
	ds_read_b128 v[196:199], v151 offset:18432
	ds_read_b128 v[200:203], v151 offset:19456
	ds_read_b128 v[204:207], v151 offset:20480
	ds_read_b128 v[208:211], v151 offset:21504
	ds_read_b128 v[212:215], v151 offset:22528
	ds_read_b128 v[216:219], v151 offset:23552
	global_load_lds_dwordx4 v[144:145], off
	s_add_i32 m0, s52, 0x2000
	s_add_u32 s52, s56, 0xb0000
	v_lshl_add_u64 v[220:221], s[56:57], 0, v[134:135]
	s_addc_u32 s53, s57, 0
	s_add_i32 s79, s71, s62
	global_load_lds_dwordx4 v[220:221], off
	v_lshl_add_u64 v[222:223], s[52:53], 0, v[130:131]
	s_mov_b32 m0, s79
	v_lshl_add_u64 v[224:225], s[58:59], 0, v[132:133]
	global_load_lds_dwordx4 v[222:223], off
	v_lshl_add_u64 v[222:223], s[52:53], 0, v[134:135]
	s_add_i32 m0, s79, 0x2000
	s_nop 0
	global_load_lds_dwordx4 v[222:223], off
	v_lshl_add_u64 v[222:223], s[58:59], 0, v[128:129]
	s_mov_b32 m0, s63
	s_nop 0
	global_load_lds_dwordx4 v[222:223], off
	s_mov_b32 m0, s64
	s_nop 0
	global_load_lds_dwordx4 v[224:225], off
	s_cmp_eq_u32 s98, 0
	s_cbranch_scc1 .Lpw8_5
	s_waitcnt vmcnt(24)
	s_branch .Lpwj_5

.LBB0_934:
	s_ashr_i32 s53, s52, 31
	s_lshl_b64 s[54:55], s[52:53], 19
	s_add_u32 s54, s80, s54
	s_addc_u32 s55, s81, s55
	s_and_b64 s[56:57], s[10:11], exec
	s_cselect_b32 s53, s55, s61
	s_cselect_b32 s83, s54, s60
	s_ashr_i32 s49, s48, 31
	s_lshl_b64 s[56:57], s[48:49], 19
	s_add_u32 s56, s66, s56
	s_addc_u32 s57, s67, s57
	s_and_b64 s[64:65], s[10:11], exec
	s_cselect_b32 s49, s57, s63
	s_cselect_b32 s84, s56, s62
	s_add_u32 s60, s60, 0x40080
	s_addc_u32 s61, s61, 0
	s_add_u32 s85, s62, 0x100
	s_addc_u32 s86, s63, 0
	s_mov_b32 s87, -2
	ds_read_b128 v[152:155], v148
	ds_read_b128 v[156:159], v148 offset:1024
	ds_read_b128 v[160:163], v148 offset:2048
	ds_read_b128 v[164:167], v148 offset:3072
	ds_read_b128 v[168:171], v149
	ds_read_b128 v[172:175], v149 offset:1024
	ds_read_b128 v[176:179], v149 offset:2048
	ds_read_b128 v[184:187], v149 offset:3072
	s_add_u32 s62, s60, 0xfffc0080
	s_addc_u32 s63, s61, -1
	s_cmp_eq_u32 s87, 12
	s_cselect_b32 s65, s53, s63
	s_cselect_b32 s64, s83, s62
	s_cselect_b32 s63, s49, s86
	s_cselect_b32 s62, s84, s85
	v_lshl_add_u64 v[220:221], s[60:61], 0, v[138:139]
	s_add_i32 m0, s69, 0xc000
	ds_read_b128 v[188:191], v150
	ds_read_b128 v[192:195], v150 offset:1024
	ds_read_b128 v[196:199], v150 offset:2048
	ds_read_b128 v[200:203], v150 offset:3072
	ds_read_b128 v[204:207], v150 offset:4096
	ds_read_b128 v[208:211], v150 offset:5120
	ds_read_b128 v[212:215], v150 offset:6144
	ds_read_b128 v[216:219], v150 offset:7168
	global_load_lds_dwordx4 v[220:221], off
	v_lshl_add_u64 v[220:221], s[60:61], 0, v[140:141]
	s_add_i32 m0, s69, 0xe000
	s_nop 0
	global_load_lds_dwordx4 v[220:221], off
	s_waitcnt vmcnt(24)
	s_waitcnt lgkmcnt(0)
	s_barrier
	s_setprio 1
	s_waitcnt lgkmcnt(0)
	v_mfma_f32_16x16x32_bf16 v[124:127], v[152:155], v[188:191], 0
	v_mfma_f32_16x16x32_bf16 v[124:127], v[156:159], v[192:195], v[124:127]
	v_mfma_f32_16x16x32_bf16 v[120:123], v[160:163], v[188:191], 0
	v_mfma_f32_16x16x32_bf16 v[120:123], v[164:167], v[192:195], v[120:123]
	v_mfma_f32_16x16x32_bf16 v[116:119], v[152:155], v[196:199], 0
	v_mfma_f32_16x16x32_bf16 v[116:119], v[156:159], v[200:203], v[116:119]
	v_mfma_f32_16x16x32_bf16 v[112:115], v[160:163], v[196:199], 0
	v_mfma_f32_16x16x32_bf16 v[112:115], v[164:167], v[200:203], v[112:115]
	v_mfma_f32_16x16x32_bf16 v[108:111], v[152:155], v[204:207], 0
	v_mfma_f32_16x16x32_bf16 v[108:111], v[156:159], v[208:211], v[108:111]
	v_mfma_f32_16x16x32_bf16 v[104:107], v[160:163], v[204:207], 0
	v_mfma_f32_16x16x32_bf16 v[104:107], v[164:167], v[208:211], v[104:107]
	v_mfma_f32_16x16x32_bf16 v[100:103], v[152:155], v[212:215], 0
	v_mfma_f32_16x16x32_bf16 v[100:103], v[156:159], v[216:219], v[100:103]
	v_mfma_f32_16x16x32_bf16 v[96:99], v[160:163], v[212:215], 0
	v_mfma_f32_16x16x32_bf16 v[96:99], v[164:167], v[216:219], v[96:99]
	v_mfma_f32_16x16x32_bf16 v[76:79], v[168:171], v[188:191], 0
	v_mfma_f32_16x16x32_bf16 v[76:79], v[172:175], v[192:195], v[76:79]
	v_mfma_f32_16x16x32_bf16 v[68:71], v[176:179], v[188:191], 0
	v_mfma_f32_16x16x32_bf16 v[68:71], v[184:187], v[192:195], v[68:71]
	v_mfma_f32_16x16x32_bf16 v[60:63], v[168:171], v[196:199], 0
	v_mfma_f32_16x16x32_bf16 v[60:63], v[172:175], v[200:203], v[60:63]
	v_mfma_f32_16x16x32_bf16 v[52:55], v[176:179], v[196:199], 0
	v_mfma_f32_16x16x32_bf16 v[52:55], v[184:187], v[200:203], v[52:55]
	v_mfma_f32_16x16x32_bf16 v[44:47], v[168:171], v[204:207], 0
	v_mfma_f32_16x16x32_bf16 v[44:47], v[172:175], v[208:211], v[44:47]
	v_mfma_f32_16x16x32_bf16 v[40:43], v[176:179], v[204:207], 0
	v_mfma_f32_16x16x32_bf16 v[40:43], v[184:187], v[208:211], v[40:43]
	v_mfma_f32_16x16x32_bf16 v[36:39], v[168:171], v[212:215], 0
	v_mfma_f32_16x16x32_bf16 v[36:39], v[172:175], v[216:219], v[36:39]
	v_mfma_f32_16x16x32_bf16 v[32:35], v[176:179], v[212:215], 0
	v_mfma_f32_16x16x32_bf16 v[32:35], v[184:187], v[216:219], v[32:35]
	s_setprio 0
	s_barrier
	s_add_i32 s79, s77, s68
	v_lshl_add_u64 v[220:221], s[62:63], 0, v[130:131]
	s_mov_b32 m0, s79
	ds_read_b128 v[188:191], v150 offset:16384
	ds_read_b128 v[192:195], v150 offset:17408
	ds_read_b128 v[196:199], v150 offset:18432
	ds_read_b128 v[200:203], v150 offset:19456
	ds_read_b128 v[204:207], v150 offset:20480
	ds_read_b128 v[208:211], v150 offset:21504
	ds_read_b128 v[212:215], v150 offset:22528
	ds_read_b128 v[216:219], v150 offset:23552
	global_load_lds_dwordx4 v[220:221], off
	s_add_i32 m0, s79, 0x2000
	s_add_u32 s88, s62, 0x40000
	v_lshl_add_u64 v[222:223], s[62:63], 0, v[134:135]
	s_addc_u32 s89, s63, 0
	s_add_i32 s79, s82, s68
	global_load_lds_dwordx4 v[222:223], off
	v_lshl_add_u64 v[224:225], s[88:89], 0, v[130:131]
	s_mov_b32 m0, s79
	v_lshl_add_u64 v[226:227], s[64:65], 0, v[132:133]
	global_load_lds_dwordx4 v[224:225], off
	v_lshl_add_u64 v[224:225], s[88:89], 0, v[134:135]
	s_add_i32 m0, s79, 0x2000
	s_nop 0
	global_load_lds_dwordx4 v[224:225], off
	v_lshl_add_u64 v[224:225], s[64:65], 0, v[128:129]
	s_mov_b32 m0, s69
	s_nop 0
	global_load_lds_dwordx4 v[224:225], off
	s_mov_b32 m0, s70
	s_nop 0
	global_load_lds_dwordx4 v[226:227], off
	s_cmp_eq_u32 s98, 0
	s_cbranch_scc1 .Lpw8_6
	s_waitcnt vmcnt(24)
	s_branch .Lpwj_6

.Lpwj_6:
	s_waitcnt lgkmcnt(0)
	s_barrier
	s_setprio 1
	s_waitcnt lgkmcnt(0)
	v_mfma_f32_16x16x32_bf16 v[92:95], v[152:155], v[188:191], 0
	v_mfma_f32_16x16x32_bf16 v[92:95], v[156:159], v[192:195], v[92:95]
	v_mfma_f32_16x16x32_bf16 v[88:91], v[160:163], v[188:191], 0
	v_mfma_f32_16x16x32_bf16 v[88:91], v[164:167], v[192:195], v[88:91]
	v_mfma_f32_16x16x32_bf16 v[84:87], v[152:155], v[196:199], 0
	v_mfma_f32_16x16x32_bf16 v[84:87], v[156:159], v[200:203], v[84:87]
	v_mfma_f32_16x16x32_bf16 v[80:83], v[160:163], v[196:199], 0
	v_mfma_f32_16x16x32_bf16 v[80:83], v[164:167], v[200:203], v[80:83]
	v_mfma_f32_16x16x32_bf16 v[72:75], v[152:155], v[204:207], 0
	v_mfma_f32_16x16x32_bf16 v[72:75], v[156:159], v[208:211], v[72:75]
	v_mfma_f32_16x16x32_bf16 v[64:67], v[160:163], v[204:207], 0
	v_mfma_f32_16x16x32_bf16 v[64:67], v[164:167], v[208:211], v[64:67]
	v_mfma_f32_16x16x32_bf16 v[56:59], v[152:155], v[212:215], 0
	v_mfma_f32_16x16x32_bf16 v[56:59], v[156:159], v[216:219], v[56:59]
	v_mfma_f32_16x16x32_bf16 v[48:51], v[160:163], v[212:215], 0
	v_mfma_f32_16x16x32_bf16 v[48:51], v[164:167], v[216:219], v[48:51]
	v_mfma_f32_16x16x32_bf16 v[28:31], v[168:171], v[188:191], 0
	v_mfma_f32_16x16x32_bf16 v[28:31], v[172:175], v[192:195], v[28:31]
	v_mfma_f32_16x16x32_bf16 v[24:27], v[176:179], v[188:191], 0
	v_mfma_f32_16x16x32_bf16 v[24:27], v[184:187], v[192:195], v[24:27]
	v_mfma_f32_16x16x32_bf16 v[20:23], v[168:171], v[196:199], 0
	v_mfma_f32_16x16x32_bf16 v[20:23], v[172:175], v[200:203], v[20:23]
	v_mfma_f32_16x16x32_bf16 v[16:19], v[176:179], v[196:199], 0
	v_mfma_f32_16x16x32_bf16 v[16:19], v[184:187], v[200:203], v[16:19]
	v_mfma_f32_16x16x32_bf16 v[12:15], v[168:171], v[204:207], 0
	v_mfma_f32_16x16x32_bf16 v[12:15], v[172:175], v[208:211], v[12:15]
	v_mfma_f32_16x16x32_bf16 v[8:11], v[176:179], v[204:207], 0
	v_mfma_f32_16x16x32_bf16 v[8:11], v[184:187], v[208:211], v[8:11]
	v_mfma_f32_16x16x32_bf16 v[4:7], v[168:171], v[212:215], 0
	v_mfma_f32_16x16x32_bf16 v[4:7], v[172:175], v[216:219], v[4:7]
	v_mfma_f32_16x16x32_bf16 v[0:3], v[176:179], v[212:215], 0
	v_mfma_f32_16x16x32_bf16 v[0:3], v[184:187], v[216:219], v[0:3]
	s_setprio 0
	s_barrier
	s_branch .Lmid_gemm6

.LBB0_950:
	s_ashr_i32 s37, s36, 31
	s_lshl_b64 s[44:45], s[36:37], 19
	s_add_u32 s44, s80, s44
	s_addc_u32 s45, s81, s45
	s_and_b64 s[46:47], s[10:11], exec
	s_cselect_b32 s37, s45, s53
	s_cselect_b32 s72, s44, s52
	s_ashr_i32 s19, s18, 31
	s_lshl_b64 s[46:47], s[18:19], 19
	s_add_u32 s46, s58, s46
	s_addc_u32 s47, s59, s47
	s_and_b64 s[56:57], s[10:11], exec
	s_cselect_b32 s19, s47, s55
	s_cselect_b32 s73, s46, s54
	s_add_u32 s52, s52, 0x40080
	s_addc_u32 s53, s53, 0
	s_add_u32 s74, s54, 0x100
	s_addc_u32 s75, s55, 0
	s_mov_b32 s76, -2
	ds_read_b128 v[140:143], v147
	ds_read_b128 v[150:153], v147 offset:1024
	ds_read_b128 v[154:157], v147 offset:2048
	ds_read_b128 v[158:161], v147 offset:3072
	ds_read_b128 v[162:165], v148
	ds_read_b128 v[166:169], v148 offset:1024
	ds_read_b128 v[170:173], v148 offset:2048
	ds_read_b128 v[174:177], v148 offset:3072
	s_add_u32 s54, s52, 0xfffc0080
	s_addc_u32 s55, s53, -1
	s_cmp_eq_u32 s76, 12
	s_cselect_b32 s57, s37, s55
	s_cselect_b32 s56, s72, s54
	s_cselect_b32 s55, s19, s75
	s_cselect_b32 s54, s73, s74
	v_lshl_add_u64 v[178:179], s[52:53], 0, v[132:133]
	s_add_i32 m0, s49, 0xc000
	ds_read_b128 v[184:187], v149
	ds_read_b128 v[188:191], v149 offset:1024
	ds_read_b128 v[192:195], v149 offset:2048
	ds_read_b128 v[196:199], v149 offset:3072
	ds_read_b128 v[200:203], v149 offset:4096
	ds_read_b128 v[204:207], v149 offset:5120
	ds_read_b128 v[208:211], v149 offset:6144
	ds_read_b128 v[212:215], v149 offset:7168
	global_load_lds_dwordx4 v[178:179], off
	v_lshl_add_u64 v[178:179], s[52:53], 0, v[134:135]
	s_add_i32 m0, s49, 0xe000
	s_nop 0
	global_load_lds_dwordx4 v[178:179], off
	s_waitcnt vmcnt(24)
	s_waitcnt lgkmcnt(0)
	s_barrier
	s_setprio 1
	s_waitcnt lgkmcnt(0)
	v_mfma_f32_16x16x32_bf16 v[124:127], v[140:143], v[184:187], 0
	v_mfma_f32_16x16x32_bf16 v[124:127], v[150:153], v[188:191], v[124:127]
	v_mfma_f32_16x16x32_bf16 v[120:123], v[154:157], v[184:187], 0
	v_mfma_f32_16x16x32_bf16 v[120:123], v[158:161], v[188:191], v[120:123]
	v_mfma_f32_16x16x32_bf16 v[108:111], v[140:143], v[192:195], 0
	v_mfma_f32_16x16x32_bf16 v[108:111], v[150:153], v[196:199], v[108:111]
	v_mfma_f32_16x16x32_bf16 v[104:107], v[154:157], v[192:195], 0
	v_mfma_f32_16x16x32_bf16 v[104:107], v[158:161], v[196:199], v[104:107]
	v_mfma_f32_16x16x32_bf16 v[92:95], v[140:143], v[200:203], 0
	v_mfma_f32_16x16x32_bf16 v[92:95], v[150:153], v[204:207], v[92:95]
	v_mfma_f32_16x16x32_bf16 v[88:91], v[154:157], v[200:203], 0
	v_mfma_f32_16x16x32_bf16 v[88:91], v[158:161], v[204:207], v[88:91]
	v_mfma_f32_16x16x32_bf16 v[76:79], v[140:143], v[208:211], 0
	v_mfma_f32_16x16x32_bf16 v[76:79], v[150:153], v[212:215], v[76:79]
	v_mfma_f32_16x16x32_bf16 v[72:75], v[154:157], v[208:211], 0
	v_mfma_f32_16x16x32_bf16 v[72:75], v[158:161], v[212:215], v[72:75]
	v_mfma_f32_16x16x32_bf16 v[116:119], v[162:165], v[184:187], 0
	v_mfma_f32_16x16x32_bf16 v[116:119], v[166:169], v[188:191], v[116:119]
	v_mfma_f32_16x16x32_bf16 v[112:115], v[170:173], v[184:187], 0
	v_mfma_f32_16x16x32_bf16 v[112:115], v[174:177], v[188:191], v[112:115]
	v_mfma_f32_16x16x32_bf16 v[100:103], v[162:165], v[192:195], 0
	v_mfma_f32_16x16x32_bf16 v[100:103], v[166:169], v[196:199], v[100:103]
	v_mfma_f32_16x16x32_bf16 v[96:99], v[170:173], v[192:195], 0
	v_mfma_f32_16x16x32_bf16 v[96:99], v[174:177], v[196:199], v[96:99]
	v_mfma_f32_16x16x32_bf16 v[84:87], v[162:165], v[200:203], 0
	v_mfma_f32_16x16x32_bf16 v[84:87], v[166:169], v[204:207], v[84:87]
	v_mfma_f32_16x16x32_bf16 v[80:83], v[170:173], v[200:203], 0
	v_mfma_f32_16x16x32_bf16 v[80:83], v[174:177], v[204:207], v[80:83]
	v_mfma_f32_16x16x32_bf16 v[68:71], v[162:165], v[208:211], 0
	v_mfma_f32_16x16x32_bf16 v[68:71], v[166:169], v[212:215], v[68:71]
	v_mfma_f32_16x16x32_bf16 v[64:67], v[170:173], v[208:211], 0
	v_mfma_f32_16x16x32_bf16 v[64:67], v[174:177], v[212:215], v[64:67]
	s_setprio 0
	s_barrier
	s_add_i32 s77, s68, s60
	v_lshl_add_u64 v[178:179], s[54:55], 0, v[130:131]
	s_mov_b32 m0, s77
	ds_read_b128 v[184:187], v149 offset:16384
	ds_read_b128 v[188:191], v149 offset:17408
	ds_read_b128 v[192:195], v149 offset:18432
	ds_read_b128 v[196:199], v149 offset:19456
	ds_read_b128 v[200:203], v149 offset:20480
	ds_read_b128 v[204:207], v149 offset:21504
	ds_read_b128 v[208:211], v149 offset:22528
	ds_read_b128 v[212:215], v149 offset:23552
	global_load_lds_dwordx4 v[178:179], off
	s_add_i32 m0, s77, 0x2000
	s_add_u32 s82, s54, 0x40000
	v_lshl_add_u64 v[216:217], s[54:55], 0, v[128:129]
	s_addc_u32 s83, s55, 0
	s_add_i32 s77, s69, s60
	global_load_lds_dwordx4 v[216:217], off
	v_lshl_add_u64 v[218:219], s[82:83], 0, v[130:131]
	s_mov_b32 m0, s77
	v_lshl_add_u64 v[220:221], s[56:57], 0, v[128:129]
	global_load_lds_dwordx4 v[218:219], off
	v_lshl_add_u64 v[218:219], s[82:83], 0, v[128:129]
	s_add_i32 m0, s77, 0x2000
	s_nop 0
	global_load_lds_dwordx4 v[218:219], off
	v_lshl_add_u64 v[218:219], s[56:57], 0, v[130:131]
	s_mov_b32 m0, s49
	s_nop 0
	global_load_lds_dwordx4 v[218:219], off
	s_mov_b32 m0, s62
	s_nop 0
	global_load_lds_dwordx4 v[220:221], off
	s_cmp_eq_u32 s98, 0
	s_cbranch_scc1 .Lpw8_7
	s_waitcnt vmcnt(24)
	s_branch .Lpwj_7

.LBB0_1030:
	s_add_u32 s86, s56, 0x100
	s_addc_u32 s87, s57, 0
	s_mov_b32 s88, -2
	ds_read_b128 v[152:155], v149
	ds_read_b128 v[156:159], v149 offset:1024
	ds_read_b128 v[160:163], v149 offset:2048
	ds_read_b128 v[164:167], v149 offset:3072
	ds_read_b128 v[168:171], v150
	ds_read_b128 v[172:175], v150 offset:1024
	ds_read_b128 v[176:179], v150 offset:2048
	ds_read_b128 v[184:187], v150 offset:3072
	s_add_u32 s56, s54, 0x100
	s_addc_u32 s57, s55, 0
	s_cmp_eq_u32 s88, 40
	s_cselect_b32 s61, s13, s57
	s_cselect_b32 s60, s12, s56
	s_cselect_b32 s59, s53, s87
	s_cselect_b32 s58, s52, s86
	v_lshl_add_u64 v[144:145], s[54:55], 0, v[136:137]
	s_add_i32 m0, s65, 0xc000
	ds_read_b128 v[188:191], v151
	ds_read_b128 v[192:195], v151 offset:1024
	ds_read_b128 v[196:199], v151 offset:2048
	ds_read_b128 v[200:203], v151 offset:3072
	ds_read_b128 v[204:207], v151 offset:4096
	ds_read_b128 v[208:211], v151 offset:5120
	ds_read_b128 v[212:215], v151 offset:6144
	ds_read_b128 v[216:219], v151 offset:7168
	global_load_lds_dwordx4 v[144:145], off
	v_lshl_add_u64 v[144:145], s[54:55], 0, v[138:139]
	s_add_i32 m0, s65, 0xe000
	s_nop 0
	global_load_lds_dwordx4 v[144:145], off
	s_waitcnt vmcnt(24)
	s_waitcnt lgkmcnt(0)
	s_barrier
	s_setprio 1
	s_waitcnt lgkmcnt(0)
	v_mfma_f32_16x16x32_bf16 v[124:127], v[152:155], v[188:191], 0
	v_mfma_f32_16x16x32_bf16 v[124:127], v[156:159], v[192:195], v[124:127]
	v_mfma_f32_16x16x32_bf16 v[120:123], v[160:163], v[188:191], 0
	v_mfma_f32_16x16x32_bf16 v[120:123], v[164:167], v[192:195], v[120:123]
	v_mfma_f32_16x16x32_bf16 v[116:119], v[152:155], v[196:199], 0
	v_mfma_f32_16x16x32_bf16 v[116:119], v[156:159], v[200:203], v[116:119]
	v_mfma_f32_16x16x32_bf16 v[108:111], v[160:163], v[196:199], 0
	v_mfma_f32_16x16x32_bf16 v[108:111], v[164:167], v[200:203], v[108:111]
	v_mfma_f32_16x16x32_bf16 v[100:103], v[152:155], v[204:207], 0
	v_mfma_f32_16x16x32_bf16 v[100:103], v[156:159], v[208:211], v[100:103]
	v_mfma_f32_16x16x32_bf16 v[92:95], v[160:163], v[204:207], 0
	v_mfma_f32_16x16x32_bf16 v[92:95], v[164:167], v[208:211], v[92:95]
	v_mfma_f32_16x16x32_bf16 v[84:87], v[152:155], v[212:215], 0
	v_mfma_f32_16x16x32_bf16 v[84:87], v[156:159], v[216:219], v[84:87]
	v_mfma_f32_16x16x32_bf16 v[76:79], v[160:163], v[212:215], 0
	v_mfma_f32_16x16x32_bf16 v[76:79], v[164:167], v[216:219], v[76:79]
	v_mfma_f32_16x16x32_bf16 v[112:115], v[168:171], v[188:191], 0
	v_mfma_f32_16x16x32_bf16 v[112:115], v[172:175], v[192:195], v[112:115]
	v_mfma_f32_16x16x32_bf16 v[104:107], v[176:179], v[188:191], 0
	v_mfma_f32_16x16x32_bf16 v[104:107], v[184:187], v[192:195], v[104:107]
	v_mfma_f32_16x16x32_bf16 v[96:99], v[168:171], v[196:199], 0
	v_mfma_f32_16x16x32_bf16 v[96:99], v[172:175], v[200:203], v[96:99]
	v_mfma_f32_16x16x32_bf16 v[88:91], v[176:179], v[196:199], 0
	v_mfma_f32_16x16x32_bf16 v[88:91], v[184:187], v[200:203], v[88:91]
	v_mfma_f32_16x16x32_bf16 v[80:83], v[168:171], v[204:207], 0
	v_mfma_f32_16x16x32_bf16 v[80:83], v[172:175], v[208:211], v[80:83]
	v_mfma_f32_16x16x32_bf16 v[72:75], v[176:179], v[204:207], 0
	v_mfma_f32_16x16x32_bf16 v[72:75], v[184:187], v[208:211], v[72:75]
	v_mfma_f32_16x16x32_bf16 v[68:71], v[168:171], v[212:215], 0
	v_mfma_f32_16x16x32_bf16 v[68:71], v[172:175], v[216:219], v[68:71]
	v_mfma_f32_16x16x32_bf16 v[64:67], v[176:179], v[212:215], 0
	v_mfma_f32_16x16x32_bf16 v[64:67], v[184:187], v[216:219], v[64:67]
	s_setprio 0
	s_barrier
	s_add_i32 s54, s72, s64
	v_lshl_add_u64 v[144:145], s[58:59], 0, v[130:131]
	s_mov_b32 m0, s54
	ds_read_b128 v[188:191], v151 offset:16384
	ds_read_b128 v[192:195], v151 offset:17408
	ds_read_b128 v[196:199], v151 offset:18432
	ds_read_b128 v[200:203], v151 offset:19456
	ds_read_b128 v[204:207], v151 offset:20480
	ds_read_b128 v[208:211], v151 offset:21504
	ds_read_b128 v[212:215], v151 offset:22528
	ds_read_b128 v[216:219], v151 offset:23552
	global_load_lds_dwordx4 v[144:145], off
	s_add_i32 m0, s54, 0x2000
	s_add_u32 s54, s58, 0xb0000
	v_lshl_add_u64 v[220:221], s[58:59], 0, v[134:135]
	s_addc_u32 s55, s59, 0
	s_add_i32 s79, s73, s64
	global_load_lds_dwordx4 v[220:221], off
	v_lshl_add_u64 v[222:223], s[54:55], 0, v[130:131]
	s_mov_b32 m0, s79
	v_lshl_add_u64 v[224:225], s[60:61], 0, v[132:133]
	global_load_lds_dwordx4 v[222:223], off
	v_lshl_add_u64 v[222:223], s[54:55], 0, v[134:135]
	s_add_i32 m0, s79, 0x2000
	s_nop 0
	global_load_lds_dwordx4 v[222:223], off
	v_lshl_add_u64 v[222:223], s[60:61], 0, v[128:129]
	s_mov_b32 m0, s65
	s_nop 0
	global_load_lds_dwordx4 v[222:223], off
	s_mov_b32 m0, s66
	s_nop 0
	global_load_lds_dwordx4 v[224:225], off
	s_cmp_eq_u32 s98, 0
	s_cbranch_scc1 .Lpw8_8
	s_waitcnt vmcnt(24)
	s_branch .Lpwj_8

.LBB0_1161:
	s_ashr_i32 s53, s52, 31
	s_lshl_b64 s[54:55], s[52:53], 19
	s_add_u32 s54, s80, s54
	s_addc_u32 s55, s81, s55
	s_and_b64 s[56:57], s[10:11], exec
	s_cselect_b32 s53, s55, s61
	s_cselect_b32 s83, s54, s60
	s_ashr_i32 s49, s48, 31
	s_lshl_b64 s[56:57], s[48:49], 19
	s_add_u32 s56, s66, s56
	s_addc_u32 s57, s67, s57
	s_and_b64 s[64:65], s[10:11], exec
	s_cselect_b32 s49, s57, s63
	s_cselect_b32 s84, s56, s62
	s_add_u32 s60, s60, 0x40080
	s_addc_u32 s61, s61, 0
	s_add_u32 s85, s62, 0x100
	s_addc_u32 s86, s63, 0
	s_mov_b32 s87, -2
	ds_read_b128 v[152:155], v148
	ds_read_b128 v[156:159], v148 offset:1024
	ds_read_b128 v[160:163], v148 offset:2048
	ds_read_b128 v[164:167], v148 offset:3072
	ds_read_b128 v[168:171], v149
	ds_read_b128 v[172:175], v149 offset:1024
	ds_read_b128 v[176:179], v149 offset:2048
	ds_read_b128 v[184:187], v149 offset:3072
	s_add_u32 s62, s60, 0xfffc0080
	s_addc_u32 s63, s61, -1
	s_cmp_eq_u32 s87, 12
	s_cselect_b32 s65, s53, s63
	s_cselect_b32 s64, s83, s62
	s_cselect_b32 s63, s49, s86
	s_cselect_b32 s62, s84, s85
	v_lshl_add_u64 v[220:221], s[60:61], 0, v[138:139]
	s_add_i32 m0, s69, 0xc000
	ds_read_b128 v[188:191], v150
	ds_read_b128 v[192:195], v150 offset:1024
	ds_read_b128 v[196:199], v150 offset:2048
	ds_read_b128 v[200:203], v150 offset:3072
	ds_read_b128 v[204:207], v150 offset:4096
	ds_read_b128 v[208:211], v150 offset:5120
	ds_read_b128 v[212:215], v150 offset:6144
	ds_read_b128 v[216:219], v150 offset:7168
	global_load_lds_dwordx4 v[220:221], off
	v_lshl_add_u64 v[220:221], s[60:61], 0, v[140:141]
	s_add_i32 m0, s69, 0xe000
	s_nop 0
	global_load_lds_dwordx4 v[220:221], off
	s_waitcnt vmcnt(24)
	s_waitcnt lgkmcnt(0)
	s_barrier
	s_setprio 1
	s_waitcnt lgkmcnt(0)
	v_mfma_f32_16x16x32_bf16 v[124:127], v[152:155], v[188:191], 0
	v_mfma_f32_16x16x32_bf16 v[124:127], v[156:159], v[192:195], v[124:127]
	v_mfma_f32_16x16x32_bf16 v[120:123], v[160:163], v[188:191], 0
	v_mfma_f32_16x16x32_bf16 v[120:123], v[164:167], v[192:195], v[120:123]
	v_mfma_f32_16x16x32_bf16 v[116:119], v[152:155], v[196:199], 0
	v_mfma_f32_16x16x32_bf16 v[116:119], v[156:159], v[200:203], v[116:119]
	v_mfma_f32_16x16x32_bf16 v[112:115], v[160:163], v[196:199], 0
	v_mfma_f32_16x16x32_bf16 v[112:115], v[164:167], v[200:203], v[112:115]
	v_mfma_f32_16x16x32_bf16 v[108:111], v[152:155], v[204:207], 0
	v_mfma_f32_16x16x32_bf16 v[108:111], v[156:159], v[208:211], v[108:111]
	v_mfma_f32_16x16x32_bf16 v[104:107], v[160:163], v[204:207], 0
	v_mfma_f32_16x16x32_bf16 v[104:107], v[164:167], v[208:211], v[104:107]
	v_mfma_f32_16x16x32_bf16 v[100:103], v[152:155], v[212:215], 0
	v_mfma_f32_16x16x32_bf16 v[100:103], v[156:159], v[216:219], v[100:103]
	v_mfma_f32_16x16x32_bf16 v[96:99], v[160:163], v[212:215], 0
	v_mfma_f32_16x16x32_bf16 v[96:99], v[164:167], v[216:219], v[96:99]
	v_mfma_f32_16x16x32_bf16 v[68:71], v[168:171], v[188:191], 0
	v_mfma_f32_16x16x32_bf16 v[68:71], v[172:175], v[192:195], v[68:71]
	v_mfma_f32_16x16x32_bf16 v[64:67], v[176:179], v[188:191], 0
	v_mfma_f32_16x16x32_bf16 v[64:67], v[184:187], v[192:195], v[64:67]
	v_mfma_f32_16x16x32_bf16 v[52:55], v[168:171], v[196:199], 0
	v_mfma_f32_16x16x32_bf16 v[52:55], v[172:175], v[200:203], v[52:55]
	v_mfma_f32_16x16x32_bf16 v[48:51], v[176:179], v[196:199], 0
	v_mfma_f32_16x16x32_bf16 v[48:51], v[184:187], v[200:203], v[48:51]
	v_mfma_f32_16x16x32_bf16 v[44:47], v[168:171], v[204:207], 0
	v_mfma_f32_16x16x32_bf16 v[44:47], v[172:175], v[208:211], v[44:47]
	v_mfma_f32_16x16x32_bf16 v[40:43], v[176:179], v[204:207], 0
	v_mfma_f32_16x16x32_bf16 v[40:43], v[184:187], v[208:211], v[40:43]
	v_mfma_f32_16x16x32_bf16 v[36:39], v[168:171], v[212:215], 0
	v_mfma_f32_16x16x32_bf16 v[36:39], v[172:175], v[216:219], v[36:39]
	v_mfma_f32_16x16x32_bf16 v[32:35], v[176:179], v[212:215], 0
	v_mfma_f32_16x16x32_bf16 v[32:35], v[184:187], v[216:219], v[32:35]
	s_setprio 0
	s_barrier
	s_add_i32 s79, s77, s68
	v_lshl_add_u64 v[220:221], s[62:63], 0, v[130:131]
	s_mov_b32 m0, s79
	ds_read_b128 v[188:191], v150 offset:16384
	ds_read_b128 v[192:195], v150 offset:17408
	ds_read_b128 v[196:199], v150 offset:18432
	ds_read_b128 v[200:203], v150 offset:19456
	ds_read_b128 v[204:207], v150 offset:20480
	ds_read_b128 v[208:211], v150 offset:21504
	ds_read_b128 v[212:215], v150 offset:22528
	ds_read_b128 v[216:219], v150 offset:23552
	global_load_lds_dwordx4 v[220:221], off
	s_add_i32 m0, s79, 0x2000
	s_add_u32 s88, s62, 0x40000
	v_lshl_add_u64 v[222:223], s[62:63], 0, v[134:135]
	s_addc_u32 s89, s63, 0
	s_add_i32 s79, s82, s68
	global_load_lds_dwordx4 v[222:223], off
	v_lshl_add_u64 v[224:225], s[88:89], 0, v[130:131]
	s_mov_b32 m0, s79
	v_lshl_add_u64 v[226:227], s[64:65], 0, v[132:133]
	global_load_lds_dwordx4 v[224:225], off
	v_lshl_add_u64 v[224:225], s[88:89], 0, v[134:135]
	s_add_i32 m0, s79, 0x2000
	s_nop 0
	global_load_lds_dwordx4 v[224:225], off
	v_lshl_add_u64 v[224:225], s[64:65], 0, v[128:129]
	s_mov_b32 m0, s69
	s_nop 0
	global_load_lds_dwordx4 v[224:225], off
	s_mov_b32 m0, s70
	s_nop 0
	global_load_lds_dwordx4 v[226:227], off
	s_cmp_eq_u32 s98, 0
	s_cbranch_scc1 .Lpw8_9
	s_waitcnt vmcnt(24)
	s_branch .Lpwj_9

.LBB0_1310:
	s_ashr_i32 s49, s48, 31
	s_lshl_b64 s[50:51], s[48:49], 19
	s_add_u32 s50, s38, s50
	s_addc_u32 s51, s39, s51
	s_and_b64 s[52:53], s[10:11], exec
	s_cselect_b32 s49, s51, s57
	s_cselect_b32 s82, s50, s56
	s_ashr_i32 s47, s46, 31
	s_lshl_b64 s[52:53], s[46:47], 19
	s_add_u32 s52, s62, s52
	s_addc_u32 s53, s63, s53
	s_and_b64 s[60:61], s[10:11], exec
	s_cselect_b32 s47, s53, s59
	s_cselect_b32 s83, s52, s58
	s_add_u32 s56, s56, 0x40080
	s_addc_u32 s57, s57, 0
	s_add_u32 s84, s58, 0x100
	s_addc_u32 s85, s59, 0
	s_mov_b32 s86, -2
	ds_read_b128 v[152:155], v149
	ds_read_b128 v[156:159], v149 offset:1024
	ds_read_b128 v[160:163], v149 offset:2048
	ds_read_b128 v[164:167], v149 offset:3072
	ds_read_b128 v[168:171], v150
	ds_read_b128 v[172:175], v150 offset:1024
	ds_read_b128 v[176:179], v150 offset:2048
	ds_read_b128 v[184:187], v150 offset:3072
	s_add_u32 s58, s56, 0xfffc0080
	s_addc_u32 s59, s57, -1
	s_cmp_eq_u32 s86, 12
	s_cselect_b32 s61, s49, s59
	s_cselect_b32 s60, s82, s58
	s_cselect_b32 s59, s47, s85
	s_cselect_b32 s58, s83, s84
	v_lshl_add_u64 v[144:145], s[56:57], 0, v[136:137]
	s_add_i32 m0, s55, 0xc000
	ds_read_b128 v[188:191], v151
	ds_read_b128 v[192:195], v151 offset:1024
	ds_read_b128 v[196:199], v151 offset:2048
	ds_read_b128 v[200:203], v151 offset:3072
	ds_read_b128 v[204:207], v151 offset:4096
	ds_read_b128 v[208:211], v151 offset:5120
	ds_read_b128 v[212:215], v151 offset:6144
	ds_read_b128 v[216:219], v151 offset:7168
	global_load_lds_dwordx4 v[144:145], off
	v_lshl_add_u64 v[144:145], s[56:57], 0, v[138:139]
	s_add_i32 m0, s55, 0xe000
	s_nop 0
	global_load_lds_dwordx4 v[144:145], off
	s_waitcnt vmcnt(24)
	s_waitcnt lgkmcnt(0)
	s_barrier
	s_setprio 1
	s_waitcnt lgkmcnt(0)
	v_mfma_f32_16x16x32_bf16 v[124:127], v[152:155], v[188:191], 0
	v_mfma_f32_16x16x32_bf16 v[124:127], v[156:159], v[192:195], v[124:127]
	v_mfma_f32_16x16x32_bf16 v[120:123], v[160:163], v[188:191], 0
	v_mfma_f32_16x16x32_bf16 v[120:123], v[164:167], v[192:195], v[120:123]
	v_mfma_f32_16x16x32_bf16 v[116:119], v[152:155], v[196:199], 0
	v_mfma_f32_16x16x32_bf16 v[116:119], v[156:159], v[200:203], v[116:119]
	v_mfma_f32_16x16x32_bf16 v[108:111], v[160:163], v[196:199], 0
	v_mfma_f32_16x16x32_bf16 v[108:111], v[164:167], v[200:203], v[108:111]
	v_mfma_f32_16x16x32_bf16 v[100:103], v[152:155], v[204:207], 0
	v_mfma_f32_16x16x32_bf16 v[100:103], v[156:159], v[208:211], v[100:103]
	v_mfma_f32_16x16x32_bf16 v[92:95], v[160:163], v[204:207], 0
	v_mfma_f32_16x16x32_bf16 v[92:95], v[164:167], v[208:211], v[92:95]
	v_mfma_f32_16x16x32_bf16 v[84:87], v[152:155], v[212:215], 0
	v_mfma_f32_16x16x32_bf16 v[84:87], v[156:159], v[216:219], v[84:87]
	v_mfma_f32_16x16x32_bf16 v[76:79], v[160:163], v[212:215], 0
	v_mfma_f32_16x16x32_bf16 v[76:79], v[164:167], v[216:219], v[76:79]
	v_mfma_f32_16x16x32_bf16 v[112:115], v[168:171], v[188:191], 0
	v_mfma_f32_16x16x32_bf16 v[112:115], v[172:175], v[192:195], v[112:115]
	v_mfma_f32_16x16x32_bf16 v[104:107], v[176:179], v[188:191], 0
	v_mfma_f32_16x16x32_bf16 v[104:107], v[184:187], v[192:195], v[104:107]
	v_mfma_f32_16x16x32_bf16 v[96:99], v[168:171], v[196:199], 0
	v_mfma_f32_16x16x32_bf16 v[96:99], v[172:175], v[200:203], v[96:99]
	v_mfma_f32_16x16x32_bf16 v[88:91], v[176:179], v[196:199], 0
	v_mfma_f32_16x16x32_bf16 v[88:91], v[184:187], v[200:203], v[88:91]
	v_mfma_f32_16x16x32_bf16 v[80:83], v[168:171], v[204:207], 0
	v_mfma_f32_16x16x32_bf16 v[80:83], v[172:175], v[208:211], v[80:83]
	v_mfma_f32_16x16x32_bf16 v[72:75], v[176:179], v[204:207], 0
	v_mfma_f32_16x16x32_bf16 v[72:75], v[184:187], v[208:211], v[72:75]
	v_mfma_f32_16x16x32_bf16 v[68:71], v[168:171], v[212:215], 0
	v_mfma_f32_16x16x32_bf16 v[68:71], v[172:175], v[216:219], v[68:71]
	v_mfma_f32_16x16x32_bf16 v[64:67], v[176:179], v[212:215], 0
	v_mfma_f32_16x16x32_bf16 v[64:67], v[184:187], v[216:219], v[64:67]
	s_setprio 0
	s_barrier
	s_add_i32 s79, s71, s64
	v_lshl_add_u64 v[144:145], s[58:59], 0, v[130:131]
	s_mov_b32 m0, s79
	ds_read_b128 v[188:191], v151 offset:16384
	ds_read_b128 v[192:195], v151 offset:17408
	ds_read_b128 v[196:199], v151 offset:18432
	ds_read_b128 v[200:203], v151 offset:19456
	ds_read_b128 v[204:207], v151 offset:20480
	ds_read_b128 v[208:211], v151 offset:21504
	ds_read_b128 v[212:215], v151 offset:22528
	ds_read_b128 v[216:219], v151 offset:23552
	global_load_lds_dwordx4 v[144:145], off
	s_add_i32 m0, s79, 0x2000
	s_add_u32 s88, s58, 0x40000
	v_lshl_add_u64 v[220:221], s[58:59], 0, v[134:135]
	s_addc_u32 s89, s59, 0
	s_add_i32 s79, s72, s64
	global_load_lds_dwordx4 v[220:221], off
	v_lshl_add_u64 v[222:223], s[88:89], 0, v[130:131]
	s_mov_b32 m0, s79
	v_lshl_add_u64 v[224:225], s[60:61], 0, v[132:133]
	global_load_lds_dwordx4 v[222:223], off
	v_lshl_add_u64 v[222:223], s[88:89], 0, v[134:135]
	s_add_i32 m0, s79, 0x2000
	s_nop 0
	global_load_lds_dwordx4 v[222:223], off
	v_lshl_add_u64 v[222:223], s[60:61], 0, v[128:129]
	s_mov_b32 m0, s55
	s_nop 0
	global_load_lds_dwordx4 v[222:223], off
	s_mov_b32 m0, s65
	s_nop 0
	global_load_lds_dwordx4 v[224:225], off
	s_cmp_eq_u32 s98, 0
	s_cbranch_scc1 .Lpw8_10
	s_waitcnt vmcnt(24)
	s_branch .Lpwj_10

.LBB0_1433:
	s_ashr_i32 s19, s18, 31
	s_lshl_b64 s[30:31], s[18:19], 19
	s_add_u32 s30, s80, s30
	s_addc_u32 s31, s81, s31
	s_and_b64 s[36:37], s[8:9], exec
	s_cselect_b32 s19, s31, s47
	s_cselect_b32 s66, s30, s46
	s_ashr_i32 s17, s16, 31
	s_lshl_b64 s[36:37], s[16:17], 19
	s_add_u32 s36, s52, s36
	s_addc_u32 s37, s53, s37
	s_and_b64 s[50:51], s[8:9], exec
	s_cselect_b32 s17, s37, s49
	s_cselect_b32 s67, s36, s48
	s_add_u32 s46, s46, 0x40080
	s_addc_u32 s47, s47, 0
	s_add_u32 s68, s48, 0x100
	s_addc_u32 s69, s49, 0
	s_mov_b32 s70, -2
	ds_read_b128 v[140:143], v147
	ds_read_b128 v[150:153], v147 offset:1024
	ds_read_b128 v[154:157], v147 offset:2048
	ds_read_b128 v[158:161], v147 offset:3072
	ds_read_b128 v[162:165], v148
	ds_read_b128 v[166:169], v148 offset:1024
	ds_read_b128 v[170:173], v148 offset:2048
	ds_read_b128 v[174:177], v148 offset:3072
	s_add_u32 s48, s46, 0xfffc0080
	s_addc_u32 s49, s47, -1
	s_cmp_eq_u32 s70, 12
	s_cselect_b32 s51, s19, s49
	s_cselect_b32 s50, s66, s48
	s_cselect_b32 s49, s17, s69
	s_cselect_b32 s48, s67, s68
	v_lshl_add_u64 v[178:179], s[46:47], 0, v[132:133]
	s_add_i32 m0, s45, 0xc000
	ds_read_b128 v[184:187], v149
	ds_read_b128 v[188:191], v149 offset:1024
	ds_read_b128 v[192:195], v149 offset:2048
	ds_read_b128 v[196:199], v149 offset:3072
	ds_read_b128 v[200:203], v149 offset:4096
	ds_read_b128 v[204:207], v149 offset:5120
	ds_read_b128 v[208:211], v149 offset:6144
	ds_read_b128 v[212:215], v149 offset:7168
	global_load_lds_dwordx4 v[178:179], off
	v_lshl_add_u64 v[178:179], s[46:47], 0, v[134:135]
	s_add_i32 m0, s45, 0xe000
	s_nop 0
	global_load_lds_dwordx4 v[178:179], off
	s_waitcnt vmcnt(24)
	s_waitcnt lgkmcnt(0)
	s_barrier
	s_setprio 1
	s_waitcnt lgkmcnt(0)
	v_mfma_f32_16x16x32_bf16 v[124:127], v[140:143], v[184:187], 0
	v_mfma_f32_16x16x32_bf16 v[124:127], v[150:153], v[188:191], v[124:127]
	v_mfma_f32_16x16x32_bf16 v[120:123], v[154:157], v[184:187], 0
	v_mfma_f32_16x16x32_bf16 v[120:123], v[158:161], v[188:191], v[120:123]
	v_mfma_f32_16x16x32_bf16 v[108:111], v[140:143], v[192:195], 0
	v_mfma_f32_16x16x32_bf16 v[108:111], v[150:153], v[196:199], v[108:111]
	v_mfma_f32_16x16x32_bf16 v[104:107], v[154:157], v[192:195], 0
	v_mfma_f32_16x16x32_bf16 v[104:107], v[158:161], v[196:199], v[104:107]
	v_mfma_f32_16x16x32_bf16 v[92:95], v[140:143], v[200:203], 0
	v_mfma_f32_16x16x32_bf16 v[92:95], v[150:153], v[204:207], v[92:95]
	v_mfma_f32_16x16x32_bf16 v[88:91], v[154:157], v[200:203], 0
	v_mfma_f32_16x16x32_bf16 v[88:91], v[158:161], v[204:207], v[88:91]
	v_mfma_f32_16x16x32_bf16 v[76:79], v[140:143], v[208:211], 0
	v_mfma_f32_16x16x32_bf16 v[76:79], v[150:153], v[212:215], v[76:79]
	v_mfma_f32_16x16x32_bf16 v[72:75], v[154:157], v[208:211], 0
	v_mfma_f32_16x16x32_bf16 v[72:75], v[158:161], v[212:215], v[72:75]
	v_mfma_f32_16x16x32_bf16 v[116:119], v[162:165], v[184:187], 0
	v_mfma_f32_16x16x32_bf16 v[116:119], v[166:169], v[188:191], v[116:119]
	v_mfma_f32_16x16x32_bf16 v[112:115], v[170:173], v[184:187], 0
	v_mfma_f32_16x16x32_bf16 v[112:115], v[174:177], v[188:191], v[112:115]
	v_mfma_f32_16x16x32_bf16 v[100:103], v[162:165], v[192:195], 0
	v_mfma_f32_16x16x32_bf16 v[100:103], v[166:169], v[196:199], v[100:103]
	v_mfma_f32_16x16x32_bf16 v[96:99], v[170:173], v[192:195], 0
	v_mfma_f32_16x16x32_bf16 v[96:99], v[174:177], v[196:199], v[96:99]
	v_mfma_f32_16x16x32_bf16 v[84:87], v[162:165], v[200:203], 0
	v_mfma_f32_16x16x32_bf16 v[84:87], v[166:169], v[204:207], v[84:87]
	v_mfma_f32_16x16x32_bf16 v[80:83], v[170:173], v[200:203], 0
	v_mfma_f32_16x16x32_bf16 v[80:83], v[174:177], v[204:207], v[80:83]
	v_mfma_f32_16x16x32_bf16 v[68:71], v[162:165], v[208:211], 0
	v_mfma_f32_16x16x32_bf16 v[68:71], v[166:169], v[212:215], v[68:71]
	v_mfma_f32_16x16x32_bf16 v[64:67], v[170:173], v[208:211], 0
	v_mfma_f32_16x16x32_bf16 v[64:67], v[174:177], v[212:215], v[64:67]
	s_setprio 0
	s_barrier
	s_add_i32 s71, s62, s54
	v_lshl_add_u64 v[178:179], s[48:49], 0, v[130:131]
	s_mov_b32 m0, s71
	ds_read_b128 v[184:187], v149 offset:16384
	ds_read_b128 v[188:191], v149 offset:17408
	ds_read_b128 v[192:195], v149 offset:18432
	ds_read_b128 v[196:199], v149 offset:19456
	ds_read_b128 v[200:203], v149 offset:20480
	ds_read_b128 v[204:207], v149 offset:21504
	ds_read_b128 v[208:211], v149 offset:22528
	ds_read_b128 v[212:215], v149 offset:23552
	global_load_lds_dwordx4 v[178:179], off
	s_add_i32 m0, s71, 0x2000
	s_add_u32 s72, s48, 0x40000
	v_lshl_add_u64 v[216:217], s[48:49], 0, v[128:129]
	s_addc_u32 s73, s49, 0
	s_add_i32 s71, s63, s54
	global_load_lds_dwordx4 v[216:217], off
	v_lshl_add_u64 v[218:219], s[72:73], 0, v[130:131]
	s_mov_b32 m0, s71
	v_lshl_add_u64 v[220:221], s[50:51], 0, v[128:129]
	global_load_lds_dwordx4 v[218:219], off
	v_lshl_add_u64 v[218:219], s[72:73], 0, v[128:129]
	s_add_i32 m0, s71, 0x2000
	s_nop 0
	global_load_lds_dwordx4 v[218:219], off
	v_lshl_add_u64 v[218:219], s[50:51], 0, v[130:131]
	s_mov_b32 m0, s45
	s_nop 0
	global_load_lds_dwordx4 v[218:219], off
	s_mov_b32 m0, s56
	s_nop 0
	global_load_lds_dwordx4 v[220:221], off
	s_cmp_eq_u32 s98, 0
	s_cbranch_scc1 .Lpw8_11
	s_waitcnt vmcnt(24)
	s_branch .Lpwj_11

.LBB0_1513:
	s_add_u32 s74, s48, 0x100
	s_addc_u32 s75, s49, 0
	s_mov_b32 s76, -2
	ds_read_b128 v[152:155], v149
	ds_read_b128 v[156:159], v149 offset:1024
	ds_read_b128 v[160:163], v149 offset:2048
	ds_read_b128 v[164:167], v149 offset:3072
	ds_read_b128 v[168:171], v150
	ds_read_b128 v[172:175], v150 offset:1024
	ds_read_b128 v[176:179], v150 offset:2048
	ds_read_b128 v[184:187], v150 offset:3072
	s_add_u32 s48, s46, 0x100
	s_addc_u32 s49, s47, 0
	s_cmp_eq_u32 s76, 40
	s_cselect_b32 s53, s9, s49
	s_cselect_b32 s52, s8, s48
	s_cselect_b32 s51, s45, s75
	s_cselect_b32 s50, s44, s74
	v_lshl_add_u64 v[144:145], s[46:47], 0, v[136:137]
	s_add_i32 m0, s57, 0xc000
	ds_read_b128 v[188:191], v151
	ds_read_b128 v[192:195], v151 offset:1024
	ds_read_b128 v[196:199], v151 offset:2048
	ds_read_b128 v[200:203], v151 offset:3072
	ds_read_b128 v[204:207], v151 offset:4096
	ds_read_b128 v[208:211], v151 offset:5120
	ds_read_b128 v[212:215], v151 offset:6144
	ds_read_b128 v[216:219], v151 offset:7168
	global_load_lds_dwordx4 v[144:145], off
	v_lshl_add_u64 v[144:145], s[46:47], 0, v[138:139]
	s_add_i32 m0, s57, 0xe000
	s_nop 0
	global_load_lds_dwordx4 v[144:145], off
	s_waitcnt vmcnt(24)
	s_waitcnt lgkmcnt(0)
	s_barrier
	s_setprio 1
	s_waitcnt lgkmcnt(0)
	v_mfma_f32_16x16x32_bf16 v[124:127], v[152:155], v[188:191], 0
	v_mfma_f32_16x16x32_bf16 v[124:127], v[156:159], v[192:195], v[124:127]
	v_mfma_f32_16x16x32_bf16 v[120:123], v[160:163], v[188:191], 0
	v_mfma_f32_16x16x32_bf16 v[120:123], v[164:167], v[192:195], v[120:123]
	v_mfma_f32_16x16x32_bf16 v[116:119], v[152:155], v[196:199], 0
	v_mfma_f32_16x16x32_bf16 v[116:119], v[156:159], v[200:203], v[116:119]
	v_mfma_f32_16x16x32_bf16 v[108:111], v[160:163], v[196:199], 0
	v_mfma_f32_16x16x32_bf16 v[108:111], v[164:167], v[200:203], v[108:111]
	v_mfma_f32_16x16x32_bf16 v[100:103], v[152:155], v[204:207], 0
	v_mfma_f32_16x16x32_bf16 v[100:103], v[156:159], v[208:211], v[100:103]
	v_mfma_f32_16x16x32_bf16 v[92:95], v[160:163], v[204:207], 0
	v_mfma_f32_16x16x32_bf16 v[92:95], v[164:167], v[208:211], v[92:95]
	v_mfma_f32_16x16x32_bf16 v[84:87], v[152:155], v[212:215], 0
	v_mfma_f32_16x16x32_bf16 v[84:87], v[156:159], v[216:219], v[84:87]
	v_mfma_f32_16x16x32_bf16 v[76:79], v[160:163], v[212:215], 0
	v_mfma_f32_16x16x32_bf16 v[76:79], v[164:167], v[216:219], v[76:79]
	v_mfma_f32_16x16x32_bf16 v[112:115], v[168:171], v[188:191], 0
	v_mfma_f32_16x16x32_bf16 v[112:115], v[172:175], v[192:195], v[112:115]
	v_mfma_f32_16x16x32_bf16 v[104:107], v[176:179], v[188:191], 0
	v_mfma_f32_16x16x32_bf16 v[104:107], v[184:187], v[192:195], v[104:107]
	v_mfma_f32_16x16x32_bf16 v[96:99], v[168:171], v[196:199], 0
	v_mfma_f32_16x16x32_bf16 v[96:99], v[172:175], v[200:203], v[96:99]
	v_mfma_f32_16x16x32_bf16 v[88:91], v[176:179], v[196:199], 0
	v_mfma_f32_16x16x32_bf16 v[88:91], v[184:187], v[200:203], v[88:91]
	v_mfma_f32_16x16x32_bf16 v[80:83], v[168:171], v[204:207], 0
	v_mfma_f32_16x16x32_bf16 v[80:83], v[172:175], v[208:211], v[80:83]
	v_mfma_f32_16x16x32_bf16 v[72:75], v[176:179], v[204:207], 0
	v_mfma_f32_16x16x32_bf16 v[72:75], v[184:187], v[208:211], v[72:75]
	v_mfma_f32_16x16x32_bf16 v[68:71], v[168:171], v[212:215], 0
	v_mfma_f32_16x16x32_bf16 v[68:71], v[172:175], v[216:219], v[68:71]
	v_mfma_f32_16x16x32_bf16 v[64:67], v[176:179], v[212:215], 0
	v_mfma_f32_16x16x32_bf16 v[64:67], v[184:187], v[216:219], v[64:67]
	s_setprio 0
	s_barrier
	s_add_i32 s46, s64, s56
	v_lshl_add_u64 v[144:145], s[50:51], 0, v[130:131]
	s_mov_b32 m0, s46
	ds_read_b128 v[188:191], v151 offset:16384
	ds_read_b128 v[192:195], v151 offset:17408
	ds_read_b128 v[196:199], v151 offset:18432
	ds_read_b128 v[200:203], v151 offset:19456
	ds_read_b128 v[204:207], v151 offset:20480
	ds_read_b128 v[208:211], v151 offset:21504
	ds_read_b128 v[212:215], v151 offset:22528
	ds_read_b128 v[216:219], v151 offset:23552
	global_load_lds_dwordx4 v[144:145], off
	s_add_i32 m0, s46, 0x2000
	s_add_u32 s46, s50, 0xb0000
	v_lshl_add_u64 v[220:221], s[50:51], 0, v[134:135]
	s_addc_u32 s47, s51, 0
	s_add_i32 s77, s65, s56
	global_load_lds_dwordx4 v[220:221], off
	v_lshl_add_u64 v[222:223], s[46:47], 0, v[130:131]
	s_mov_b32 m0, s77
	v_lshl_add_u64 v[224:225], s[52:53], 0, v[132:133]
	global_load_lds_dwordx4 v[222:223], off
	v_lshl_add_u64 v[222:223], s[46:47], 0, v[134:135]
	s_add_i32 m0, s77, 0x2000
	s_nop 0
	global_load_lds_dwordx4 v[222:223], off
	v_lshl_add_u64 v[222:223], s[52:53], 0, v[128:129]
	s_mov_b32 m0, s57
	s_nop 0
	global_load_lds_dwordx4 v[222:223], off
	s_mov_b32 m0, s58
	s_nop 0
	global_load_lds_dwordx4 v[224:225], off
	s_cmp_eq_u32 s98, 0
	s_cbranch_scc1 .Lpw8_12
	s_waitcnt vmcnt(24)
	s_branch .Lpwj_12
